# PW1: wave-specialised phase 1: waves 0-3 run the weight-product unit for tid and tid+256 while waves 4-7 convert the remaining x rows [32768,49152) (same 3 workgroup barriers)
# speedup vs baseline: 1.0094x; 1.0094x over previous
; #define LAS __attribute__((address_space(3)))
; __device__ void p_weights_prod(const Args& a, LAS unsigned char* lds) {
;     ...
;     for (int u = blockIdx.x; u < 256; u += gridDim.x) {
;         const int l = u >> 7, g = (u >> 5) & 3, kblk = u & 31, pn = 7 + g;
;         __syncthreads();
;         {
;             const int rr = tid >> 4, c8 = (tid & 15) * 8;
;             const float* src = a.w_in + (size_t)l * DM * INW + (size_t)(kblk * 32 + rr) * INW + 1280 + g * 128 + c8;
;             const f32x4* msrc = (const f32x4*)(MM + (size_t)(l * 4 + g) * 128 * 256) + tid;
;             f32x4 mreg[16];
; #pragma unroll
;             for (int j = 0; j < 16; ++j) mreg[j] = msrc[j * NTHREADS];
;             *(LAS f32x4*)(wt + rr * 128 + c8) = *(const f32x4*)src; *(LAS f32x4*)(wt + rr * 128 + c8 + 4) = *(const f32x4*)(src + 4);
.LBB0_86:
.LBB0_87:
	v_readfirstlane_b32 s100, v0
	s_nop 3
	s_cmp_ge_u32 s100, 0x100
	s_cbranch_scc1 .Lpw_x
	v_mov_b32_e32 v8, v0
	v_lshlrev_b32_e32 v10, 4, v8
	s_load_dword s9, s[0:1], 0x60
	s_add_u32 s6, s40, 0x1fb00000
	v_lshlrev_b32_e32 v1, 1, v8
	v_and_b32_e32 v2, 0x90, v10
	s_movk_i32 s3, 0x6c
	v_lshlrev_b32_e32 v3, 3, v8
	v_ashrrev_i32_e32 v9, 31, v8
	s_addc_u32 s7, s41, 0
	v_and_or_b32 v2, v1, s3, v2
	v_ashrrev_i32_e32 v11, 6, v8
	v_ashrrev_i32_e32 v1, 4, v8
	v_and_b32_e32 v4, 0x78, v3
	v_lshl_add_u64 v[6:7], v[8:9], 4, s[40:41]
	s_mov_b64 s[4:5], 0x20a00000
	v_and_b32_e32 v8, 63, v8
	v_lshl_add_u64 v[6:7], v[6:7], 0, s[4:5]
	v_lshlrev_b32_e32 v3, 9, v1
	v_lshlrev_b32_e32 v9, 2, v4
	v_add_u32_e32 v24, 0, v10
	s_add_u32 s4, s0, 0x60
	v_lshl_add_u32 v8, v8, 4, 0
	v_mov_b32_e32 v5, 0
	s_mov_b32 s11, 0
	v_add3_u32 v3, 0, v3, v9
	s_movk_i32 s3, 0x4000
	v_add_u32_e32 v25, 0x4000, v24
	v_lshl_add_u32 v26, v11, 11, 0
	v_lshlrev_b32_e32 v27, 2, v11
	s_addc_u32 s5, s1, 0
	s_mov_b32 s14, 0x14000
	v_add_u32_e32 v28, 0x14000, v24
	s_mov_b32 s15, 0x16000
	v_add_u32_e32 v29, 0x16000, v24
	s_mov_b32 s33, 0x18000
	v_add_u32_e32 v30, 0x18000, v24
	s_mov_b32 s34, 0x1a000
	v_add_u32_e32 v31, 0x1a000, v24
	s_mov_b32 s35, 0x1c000
	v_add_u32_e32 v32, 0x1c000, v24
	s_mov_b32 s36, 0x1e000
	v_add_u32_e32 v33, 0x1e000, v24
	v_add_u32_e32 v34, 0x20000, v24
	v_add_u32_e32 v35, 0x22000, v24
	v_add_u32_e32 v36, 0x4000, v8
	s_movk_i32 s37, 0x2400
	s_movk_i32 s44, 0x2000
	s_movk_i32 s45, 0x6000
	s_mov_b32 s46, 0x8000
	s_mov_b32 s47, 0xa000
	s_mov_b32 s48, 0xc000
	s_mov_b32 s49, 0xe000
	s_mov_b32 s50, 0x10000
	s_mov_b32 s51, 0x12000
	v_lshlrev_b32_e32 v4, 2, v4
	s_mov_b64 s[12:13], 0x1400
	s_movk_i32 s52, 0x1000
	s_mov_b32 s53, s2
	s_ashr_i32 s55, s53, 7
	s_bfe_u32 s54, s53, 0x20005
	s_mul_i32 s56, s55, 0x900000
	s_mul_hi_i32 s10, s55, 0x900000
	s_add_u32 s58, s22, s56
	s_addc_u32 s59, s23, s10
	s_lshl_b32 s10, s53, 5
	s_and_b32 s56, s10, 0x3e0
	v_add_u32_e32 v10, s56, v1
	v_mov_b64_e32 v[8:9], s[58:59]
	v_mad_i64_i32 v[8:9], s[58:59], v10, s37, v[8:9]
	s_lshl_b32 s10, s54, 9
	v_lshl_add_u64 v[8:9], v[8:9], 0, s[10:11]
	s_lshl_b32 s10, s55, 2
	s_or_b32 s58, s10, s54
	v_lshl_add_u64 v[8:9], v[8:9], 0, v[4:5]
	s_ashr_i32 s59, s58, 31
	v_add_co_u32_e32 v10, vcc, s52, v8
	s_lshl_b64 s[58:59], s[58:59], 17
	s_nop 0
	v_addc_co_u32_e32 v11, vcc, 0, v9, vcc
	v_lshl_add_u64 v[86:87], v[6:7], 0, s[58:59]
	v_add_co_u32_e32 v20, vcc, s44, v86
	v_lshl_add_u64 v[12:13], v[8:9], 0, s[12:13]
	s_nop 0
	v_addc_co_u32_e32 v21, vcc, 0, v87, vcc
	v_add_co_u32_e32 v38, vcc, s3, v86
	s_waitcnt lgkmcnt(0)
	s_nop 0
	v_addc_co_u32_e32 v39, vcc, 0, v87, vcc
	v_add_co_u32_e32 v42, vcc, s45, v86
	s_barrier
	s_nop 0
	v_addc_co_u32_e32 v43, vcc, 0, v87, vcc
	v_add_co_u32_e32 v46, vcc, s46, v86
	s_nop 1
	v_addc_co_u32_e32 v47, vcc, 0, v87, vcc
	v_add_co_u32_e32 v50, vcc, s47, v86
	global_load_dwordx4 v[8:11], v[10:11], off offset:1024
	s_nop 0
	global_load_dwordx4 v[12:15], v[12:13], off offset:16
	v_addc_co_u32_e32 v51, vcc, 0, v87, vcc
	v_add_co_u32_e32 v54, vcc, s48, v86
	global_load_dwordx4 v[16:19], v[86:87], off
	s_nop 0
	global_load_dwordx4 v[20:23], v[20:21], off
	v_addc_co_u32_e32 v55, vcc, 0, v87, vcc
	v_add_co_u32_e32 v58, vcc, s49, v86
	global_load_dwordx4 v[38:41], v[38:39], off
	s_nop 0
	global_load_dwordx4 v[42:45], v[42:43], off
	v_addc_co_u32_e32 v59, vcc, 0, v87, vcc
	v_add_co_u32_e32 v62, vcc, s50, v86
	global_load_dwordx4 v[46:49], v[46:47], off
	s_nop 0
	global_load_dwordx4 v[50:53], v[50:51], off
	v_addc_co_u32_e32 v63, vcc, 0, v87, vcc
	v_add_co_u32_e32 v66, vcc, s51, v86
	s_mov_b32 s10, -4
	s_nop 0
	v_addc_co_u32_e32 v67, vcc, 0, v87, vcc
	v_add_co_u32_e32 v70, vcc, s14, v86
	v_mov_b32_e32 v37, v26
	s_nop 0
	v_addc_co_u32_e32 v71, vcc, 0, v87, vcc
	v_add_co_u32_e32 v74, vcc, s15, v86
	s_nop 1
	v_addc_co_u32_e32 v75, vcc, 0, v87, vcc
	v_add_co_u32_e32 v78, vcc, s33, v86
	global_load_dwordx4 v[54:57], v[54:55], off
	s_nop 0
	global_load_dwordx4 v[58:61], v[58:59], off
	s_nop 0
	global_load_dwordx4 v[62:65], v[62:63], off
	s_nop 0
	global_load_dwordx4 v[66:69], v[66:67], off
	s_nop 0
	global_load_dwordx4 v[70:73], v[70:71], off
	s_nop 0
	global_load_dwordx4 v[74:77], v[74:75], off
	v_addc_co_u32_e32 v79, vcc, 0, v87, vcc
	v_add_co_u32_e32 v82, vcc, s34, v86
	s_nop 1
	v_addc_co_u32_e32 v83, vcc, 0, v87, vcc
	v_add_co_u32_e32 v88, vcc, s35, v86
	global_load_dwordx4 v[78:81], v[78:79], off
	s_nop 0
	global_load_dwordx4 v[82:85], v[82:83], off
	v_addc_co_u32_e32 v89, vcc, 0, v87, vcc
	v_add_co_u32_e32 v90, vcc, s36, v86
	s_nop 1
	v_addc_co_u32_e32 v91, vcc, 0, v87, vcc
	global_load_dwordx4 v[86:89], v[88:89], off
	s_nop 0
	global_load_dwordx4 v[90:93], v[90:91], off
	s_waitcnt vmcnt(0)
; #define LAS __attribute__((address_space(3)))
; __device__ void p_weights_prod(const Args& a, LAS unsigned char* lds) {
;     ...
;             *(LAS f32x4*)(wt + rr * 128 + c8) = *(const f32x4*)src; *(LAS f32x4*)(wt + rr * 128 + c8 + 4) = *(const f32x4*)(src + 4);
; #pragma unroll
;             for (int j = 0; j < 16; ++j) ((LAS f32x4*)mmt)[tid + j * NTHREADS] = mreg[j];
;         }
;         __syncthreads();
;         f32x4 acc[4];
; #pragma unroll
;         for (int r2 = 0; r2 < 4; ++r2) acc[r2] = (f32x4){0.f, 0.f, 0.f, 0.f};
	ds_write_b128 v3, v[8:11]
	ds_write_b128 v3, v[12:15] offset:16
	ds_write_b128 v24, v[16:19] offset:16384
	ds_write_b128 v24, v[20:23] offset:24576
	ds_write_b128 v24, v[38:41] offset:32768
	ds_write_b128 v24, v[42:45] offset:40960
	ds_write_b128 v24, v[46:49] offset:49152
	ds_write_b128 v24, v[50:53] offset:57344
	ds_write_b128 v25, v[54:57] offset:49152
	ds_write_b128 v25, v[58:61] offset:57344
	ds_write_b128 v28, v[62:65]
	ds_write_b128 v29, v[66:69]
	ds_write_b128 v30, v[70:73]
	ds_write_b128 v31, v[74:77]
	ds_write_b128 v32, v[78:81]
	ds_write_b128 v33, v[82:85]
	ds_write_b128 v34, v[86:89]
	ds_write_b128 v35, v[90:93]
	v_mov_b32_e32 v38, v36
	v_mov_b32_e32 v10, 0
	v_mov_b32_e32 v11, v5
	v_mov_b32_e32 v8, 0
	v_mov_b32_e32 v9, v5
	v_mov_b32_e32 v22, 0
	v_mov_b32_e32 v23, v5
	v_mov_b32_e32 v20, 0
	v_mov_b32_e32 v21, v5
	v_mov_b32_e32 v14, 0
	v_mov_b32_e32 v15, v5
	v_mov_b32_e32 v12, 0
	v_mov_b32_e32 v13, v5
	v_mov_b32_e32 v18, 0
	v_mov_b32_e32 v19, v5
	v_mov_b32_e32 v16, 0
	v_mov_b32_e32 v17, v5
	v_add_u32_e32 v0, 0x100, v0
	v_mov_b32_e32 v8, v0
	v_lshlrev_b32_e32 v10, 4, v8
	s_load_dword s9, s[0:1], 0x60
	s_add_u32 s6, s40, 0x1fb00000
	v_lshlrev_b32_e32 v1, 1, v8
	v_and_b32_e32 v2, 0x90, v10
	s_movk_i32 s3, 0x6c
	v_lshlrev_b32_e32 v3, 3, v8
	v_ashrrev_i32_e32 v9, 31, v8
	s_addc_u32 s7, s41, 0
	v_and_or_b32 v2, v1, s3, v2
	v_ashrrev_i32_e32 v11, 6, v8
	v_ashrrev_i32_e32 v1, 4, v8
	v_and_b32_e32 v4, 0x78, v3
	v_lshl_add_u64 v[6:7], v[8:9], 4, s[40:41]
	s_mov_b64 s[4:5], 0x20a00000
	v_and_b32_e32 v8, 63, v8
	v_lshl_add_u64 v[6:7], v[6:7], 0, s[4:5]
	v_lshlrev_b32_e32 v3, 9, v1
	v_lshlrev_b32_e32 v9, 2, v4
	v_add_u32_e32 v24, 0, v10
	s_add_u32 s4, s0, 0x60
	v_lshl_add_u32 v8, v8, 4, 0
	v_mov_b32_e32 v5, 0
	s_mov_b32 s11, 0
	v_add3_u32 v3, 0, v3, v9
	s_movk_i32 s3, 0x4000
	v_add_u32_e32 v25, 0x4000, v24
	v_lshl_add_u32 v26, v11, 11, 0
	v_lshlrev_b32_e32 v27, 2, v11
	s_addc_u32 s5, s1, 0
	s_mov_b32 s14, 0x14000
	v_add_u32_e32 v28, 0x14000, v24
	s_mov_b32 s15, 0x16000
	v_add_u32_e32 v29, 0x16000, v24
	s_mov_b32 s33, 0x18000
	v_add_u32_e32 v30, 0x18000, v24
	s_mov_b32 s34, 0x1a000
	v_add_u32_e32 v31, 0x1a000, v24
	s_mov_b32 s35, 0x1c000
	v_add_u32_e32 v32, 0x1c000, v24
	s_mov_b32 s36, 0x1e000
	v_add_u32_e32 v33, 0x1e000, v24
	v_add_u32_e32 v34, 0x20000, v24
	v_add_u32_e32 v35, 0x22000, v24
	v_add_u32_e32 v36, 0x4000, v8
	s_movk_i32 s37, 0x2400
	s_movk_i32 s44, 0x2000
	s_movk_i32 s45, 0x6000
	s_mov_b32 s46, 0x8000
	s_mov_b32 s47, 0xa000
	s_mov_b32 s48, 0xc000
	s_mov_b32 s49, 0xe000
	s_mov_b32 s50, 0x10000
	s_mov_b32 s51, 0x12000
	v_lshlrev_b32_e32 v4, 2, v4
	s_mov_b64 s[12:13], 0x1400
	s_movk_i32 s52, 0x1000
	s_mov_b32 s53, s2
	s_ashr_i32 s55, s53, 7
	s_bfe_u32 s54, s53, 0x20005
	s_mul_i32 s56, s55, 0x900000
	s_mul_hi_i32 s10, s55, 0x900000
	s_add_u32 s58, s22, s56
	s_addc_u32 s59, s23, s10
	s_lshl_b32 s10, s53, 5
	s_and_b32 s56, s10, 0x3e0
	v_add_u32_e32 v10, s56, v1
	v_mov_b64_e32 v[8:9], s[58:59]
	v_mad_i64_i32 v[8:9], s[58:59], v10, s37, v[8:9]
	s_lshl_b32 s10, s54, 9
	v_lshl_add_u64 v[8:9], v[8:9], 0, s[10:11]
	s_lshl_b32 s10, s55, 2
	s_or_b32 s58, s10, s54
	v_lshl_add_u64 v[8:9], v[8:9], 0, v[4:5]
	s_ashr_i32 s59, s58, 31
	v_add_co_u32_e32 v10, vcc, s52, v8
	s_lshl_b64 s[58:59], s[58:59], 17
	s_nop 0
	v_addc_co_u32_e32 v11, vcc, 0, v9, vcc
	v_lshl_add_u64 v[86:87], v[6:7], 0, s[58:59]
	v_add_co_u32_e32 v20, vcc, s44, v86
	v_lshl_add_u64 v[12:13], v[8:9], 0, s[12:13]
	s_nop 0
	v_addc_co_u32_e32 v21, vcc, 0, v87, vcc
	v_add_co_u32_e32 v38, vcc, s3, v86
	s_waitcnt lgkmcnt(0)
	s_nop 0
	v_addc_co_u32_e32 v39, vcc, 0, v87, vcc
	v_add_co_u32_e32 v42, vcc, s45, v86
	s_nop 0
	v_addc_co_u32_e32 v43, vcc, 0, v87, vcc
	v_add_co_u32_e32 v46, vcc, s46, v86
	s_nop 1
	v_addc_co_u32_e32 v47, vcc, 0, v87, vcc
	v_add_co_u32_e32 v50, vcc, s47, v86
	global_load_dwordx4 v[8:11], v[10:11], off offset:1024
	s_nop 0
	global_load_dwordx4 v[12:15], v[12:13], off offset:16
	v_addc_co_u32_e32 v51, vcc, 0, v87, vcc
	v_add_co_u32_e32 v54, vcc, s48, v86
	global_load_dwordx4 v[16:19], v[86:87], off
	s_nop 0
	global_load_dwordx4 v[20:23], v[20:21], off
	v_addc_co_u32_e32 v55, vcc, 0, v87, vcc
	v_add_co_u32_e32 v58, vcc, s49, v86
	global_load_dwordx4 v[38:41], v[38:39], off
	s_nop 0
	global_load_dwordx4 v[42:45], v[42:43], off
	v_addc_co_u32_e32 v59, vcc, 0, v87, vcc
	v_add_co_u32_e32 v62, vcc, s50, v86
	global_load_dwordx4 v[46:49], v[46:47], off
	s_nop 0
	global_load_dwordx4 v[50:53], v[50:51], off
	v_addc_co_u32_e32 v63, vcc, 0, v87, vcc
	v_add_co_u32_e32 v66, vcc, s51, v86
	s_mov_b32 s10, -4
	s_nop 0
	v_addc_co_u32_e32 v67, vcc, 0, v87, vcc
	v_add_co_u32_e32 v70, vcc, s14, v86
	v_mov_b32_e32 v37, v26
	s_nop 0
	v_addc_co_u32_e32 v71, vcc, 0, v87, vcc
	v_add_co_u32_e32 v74, vcc, s15, v86
	s_nop 1
	v_addc_co_u32_e32 v75, vcc, 0, v87, vcc
	v_add_co_u32_e32 v78, vcc, s33, v86
	global_load_dwordx4 v[54:57], v[54:55], off
	s_nop 0
	global_load_dwordx4 v[58:61], v[58:59], off
	s_nop 0
	global_load_dwordx4 v[62:65], v[62:63], off
	s_nop 0
	global_load_dwordx4 v[66:69], v[66:67], off
	s_nop 0
	global_load_dwordx4 v[70:73], v[70:71], off
	s_nop 0
	global_load_dwordx4 v[74:77], v[74:75], off
	v_addc_co_u32_e32 v79, vcc, 0, v87, vcc
	v_add_co_u32_e32 v82, vcc, s34, v86
	s_nop 1
	v_addc_co_u32_e32 v83, vcc, 0, v87, vcc
	v_add_co_u32_e32 v88, vcc, s35, v86
	global_load_dwordx4 v[78:81], v[78:79], off
	s_nop 0
	global_load_dwordx4 v[82:85], v[82:83], off
	v_addc_co_u32_e32 v89, vcc, 0, v87, vcc
	v_add_co_u32_e32 v90, vcc, s36, v86
	s_nop 1
	v_addc_co_u32_e32 v91, vcc, 0, v87, vcc
	global_load_dwordx4 v[86:89], v[88:89], off
	s_nop 0
	global_load_dwordx4 v[90:93], v[90:91], off
	s_waitcnt vmcnt(0)
	ds_write_b128 v3, v[8:11]
	ds_write_b128 v3, v[12:15] offset:16
	ds_write_b128 v24, v[16:19] offset:16384
	ds_write_b128 v24, v[20:23] offset:24576
	ds_write_b128 v24, v[38:41] offset:32768
	ds_write_b128 v24, v[42:45] offset:40960
	ds_write_b128 v24, v[46:49] offset:49152
	ds_write_b128 v24, v[50:53] offset:57344
	ds_write_b128 v25, v[54:57] offset:49152
	ds_write_b128 v25, v[58:61] offset:57344
	ds_write_b128 v28, v[62:65]
	ds_write_b128 v29, v[66:69]
	ds_write_b128 v30, v[70:73]
	ds_write_b128 v31, v[74:77]
	ds_write_b128 v32, v[78:81]
	ds_write_b128 v33, v[82:85]
	ds_write_b128 v34, v[86:89]
	ds_write_b128 v35, v[90:93]
	v_mov_b32_e32 v38, v36
	v_mov_b32_e32 v10, 0
	v_mov_b32_e32 v11, v5
	v_mov_b32_e32 v8, 0
	v_mov_b32_e32 v9, v5
	v_mov_b32_e32 v22, 0
	v_mov_b32_e32 v23, v5
	v_mov_b32_e32 v20, 0
	v_mov_b32_e32 v21, v5
	v_mov_b32_e32 v14, 0
	v_mov_b32_e32 v15, v5
	v_mov_b32_e32 v12, 0
	v_mov_b32_e32 v13, v5
	v_mov_b32_e32 v18, 0
	v_mov_b32_e32 v19, v5
	v_mov_b32_e32 v16, 0
	v_mov_b32_e32 v17, v5
	s_waitcnt lgkmcnt(0)
	s_barrier
; #define LAS __attribute__((address_space(3)))
; __device__ void p_weights_prod(const Args& a, LAS unsigned char* lds) {
;     ...
;         f32x4 acc[4];
; #pragma unroll
;         for (int r2 = 0; r2 < 4; ++r2) acc[r2] = (f32x4){0.f, 0.f, 0.f, 0.f};
; #pragma unroll 2
;         for (int c0 = 0; c0 < 128; c0 += 4) {
;             f32x4 w4[4], m4[4];
; #pragma unroll
;             for (int r2 = 0; r2 < 4; ++r2) w4[r2] = *(const LAS f32x4*)(wt + (4 * rq + r2) * 128 + c0);
; #pragma unroll
;             for (int cc = 0; cc < 4; ++cc) m4[cc] = *(const LAS f32x4*)(mmt + (c0 + cc) * 256 + lc0);
; #pragma unroll
;             for (int r2 = 0; r2 < 4; ++r2)
; #pragma unroll
;                 for (int cc = 0; cc < 4; ++cc) acc[r2] += m4[cc] * w4[r2][cc];
;         }
	v_add_u32_e32 v0, 0xffffff00, v0
	v_mov_b32_e32 v8, v0
	v_lshlrev_b32_e32 v10, 4, v8
	s_load_dword s9, s[0:1], 0x60
	s_add_u32 s6, s40, 0x1fb00000
	v_lshlrev_b32_e32 v1, 1, v8
	v_and_b32_e32 v2, 0x90, v10
	s_movk_i32 s3, 0x6c
	v_lshlrev_b32_e32 v3, 3, v8
	v_ashrrev_i32_e32 v9, 31, v8
	s_addc_u32 s7, s41, 0
	v_and_or_b32 v2, v1, s3, v2
	v_ashrrev_i32_e32 v11, 6, v8
	v_ashrrev_i32_e32 v1, 4, v8
	v_and_b32_e32 v4, 0x78, v3
	v_lshl_add_u64 v[6:7], v[8:9], 4, s[40:41]
	s_mov_b64 s[4:5], 0x20a00000
	v_and_b32_e32 v8, 63, v8
	v_lshl_add_u64 v[6:7], v[6:7], 0, s[4:5]
	v_lshlrev_b32_e32 v3, 9, v1
	v_lshlrev_b32_e32 v9, 2, v4
	v_add_u32_e32 v24, 0, v10
	s_add_u32 s4, s0, 0x60
	v_lshl_add_u32 v8, v8, 4, 0
	v_mov_b32_e32 v5, 0
	s_mov_b32 s11, 0
	v_add3_u32 v3, 0, v3, v9
	s_movk_i32 s3, 0x4000
	v_add_u32_e32 v25, 0x4000, v24
	v_lshl_add_u32 v26, v11, 11, 0
	v_lshlrev_b32_e32 v27, 2, v11
	s_addc_u32 s5, s1, 0
	s_mov_b32 s14, 0x14000
	v_add_u32_e32 v28, 0x14000, v24
	s_mov_b32 s15, 0x16000
	v_add_u32_e32 v29, 0x16000, v24
	s_mov_b32 s33, 0x18000
	v_add_u32_e32 v30, 0x18000, v24
	s_mov_b32 s34, 0x1a000
	v_add_u32_e32 v31, 0x1a000, v24
	s_mov_b32 s35, 0x1c000
	v_add_u32_e32 v32, 0x1c000, v24
	s_mov_b32 s36, 0x1e000
	v_add_u32_e32 v33, 0x1e000, v24
	v_add_u32_e32 v34, 0x20000, v24
	v_add_u32_e32 v35, 0x22000, v24
	v_add_u32_e32 v36, 0x4000, v8
	s_movk_i32 s37, 0x2400
	s_movk_i32 s44, 0x2000
	s_movk_i32 s45, 0x6000
	s_mov_b32 s46, 0x8000
	s_mov_b32 s47, 0xa000
	s_mov_b32 s48, 0xc000
	s_mov_b32 s49, 0xe000
	s_mov_b32 s50, 0x10000
	s_mov_b32 s51, 0x12000
	v_lshlrev_b32_e32 v4, 2, v4
	s_mov_b64 s[12:13], 0x1400
	s_movk_i32 s52, 0x1000
	s_mov_b32 s53, s2
	s_ashr_i32 s55, s53, 7
	s_bfe_u32 s54, s53, 0x20005
	s_mul_i32 s56, s55, 0x900000
	s_mul_hi_i32 s10, s55, 0x900000
	s_add_u32 s58, s22, s56
	s_addc_u32 s59, s23, s10
	s_lshl_b32 s10, s53, 5
	s_and_b32 s56, s10, 0x3e0
	v_add_u32_e32 v10, s56, v1
	v_mov_b64_e32 v[8:9], s[58:59]
	v_mad_i64_i32 v[8:9], s[58:59], v10, s37, v[8:9]
	s_lshl_b32 s10, s54, 9
	v_lshl_add_u64 v[8:9], v[8:9], 0, s[10:11]
	s_lshl_b32 s10, s55, 2
	s_or_b32 s58, s10, s54
	v_lshl_add_u64 v[8:9], v[8:9], 0, v[4:5]
	s_ashr_i32 s59, s58, 31
	v_add_co_u32_e32 v10, vcc, s52, v8
	s_lshl_b64 s[58:59], s[58:59], 17
	s_nop 0
	v_addc_co_u32_e32 v11, vcc, 0, v9, vcc
	v_lshl_add_u64 v[86:87], v[6:7], 0, s[58:59]
	v_add_co_u32_e32 v20, vcc, s44, v86
	v_lshl_add_u64 v[12:13], v[8:9], 0, s[12:13]
	s_nop 0
	v_addc_co_u32_e32 v21, vcc, 0, v87, vcc
	v_add_co_u32_e32 v38, vcc, s3, v86
	s_waitcnt lgkmcnt(0)
	s_nop 0
	v_addc_co_u32_e32 v39, vcc, 0, v87, vcc
	v_add_co_u32_e32 v42, vcc, s45, v86
	s_nop 0
	v_addc_co_u32_e32 v43, vcc, 0, v87, vcc
	v_add_co_u32_e32 v46, vcc, s46, v86
	s_nop 1
	v_addc_co_u32_e32 v47, vcc, 0, v87, vcc
	v_add_co_u32_e32 v50, vcc, s47, v86
	s_nop 0
	v_addc_co_u32_e32 v51, vcc, 0, v87, vcc
	v_add_co_u32_e32 v54, vcc, s48, v86
	s_nop 0
	v_addc_co_u32_e32 v55, vcc, 0, v87, vcc
	v_add_co_u32_e32 v58, vcc, s49, v86
	s_nop 0
	v_addc_co_u32_e32 v59, vcc, 0, v87, vcc
	v_add_co_u32_e32 v62, vcc, s50, v86
	s_nop 0
	v_addc_co_u32_e32 v63, vcc, 0, v87, vcc
	v_add_co_u32_e32 v66, vcc, s51, v86
	s_mov_b32 s10, -4
	s_nop 0
	v_addc_co_u32_e32 v67, vcc, 0, v87, vcc
	v_add_co_u32_e32 v70, vcc, s14, v86
	v_mov_b32_e32 v37, v26
	s_nop 0
	v_addc_co_u32_e32 v71, vcc, 0, v87, vcc
	v_add_co_u32_e32 v74, vcc, s15, v86
	s_nop 1
	v_addc_co_u32_e32 v75, vcc, 0, v87, vcc
	v_add_co_u32_e32 v78, vcc, s33, v86
	s_nop 0
	s_nop 0
	s_nop 0
	s_nop 0
	s_nop 0
	v_addc_co_u32_e32 v79, vcc, 0, v87, vcc
	v_add_co_u32_e32 v82, vcc, s34, v86
	s_nop 1
	v_addc_co_u32_e32 v83, vcc, 0, v87, vcc
	v_add_co_u32_e32 v88, vcc, s35, v86
	s_nop 0
	v_addc_co_u32_e32 v89, vcc, 0, v87, vcc
	v_add_co_u32_e32 v90, vcc, s36, v86
	s_nop 1
	v_addc_co_u32_e32 v91, vcc, 0, v87, vcc
	s_nop 0
	s_waitcnt vmcnt(0)
	v_mov_b32_e32 v38, v36
	v_mov_b32_e32 v10, 0
	v_mov_b32_e32 v11, v5
	v_mov_b32_e32 v8, 0
	v_mov_b32_e32 v9, v5
	v_mov_b32_e32 v22, 0
	v_mov_b32_e32 v23, v5
	v_mov_b32_e32 v20, 0
	v_mov_b32_e32 v21, v5
	v_mov_b32_e32 v14, 0
	v_mov_b32_e32 v15, v5
	v_mov_b32_e32 v12, 0
	v_mov_b32_e32 v13, v5
	v_mov_b32_e32 v18, 0
	v_mov_b32_e32 v19, v5
	v_mov_b32_e32 v16, 0
	v_mov_b32_e32 v17, v5
.Lpw_ka:
	ds_read_b128 v[40:43], v38
	ds_read_b128 v[44:47], v38 offset:1024
	ds_read_b128 v[48:51], v38 offset:2048
	ds_read_b128 v[52:55], v38 offset:3072
	ds_read_b128 v[56:59], v37
	ds_read_b128 v[60:63], v37 offset:16
	ds_read_b128 v[64:67], v37 offset:512
	ds_read_b128 v[68:71], v37 offset:528
	ds_read_b128 v[72:75], v37 offset:1024
	ds_read_b128 v[76:79], v37 offset:1040
	ds_read_b128 v[80:83], v37 offset:1536
	ds_read_b128 v[84:87], v37 offset:1552
	ds_read_b128 v[88:91], v38 offset:4096
	ds_read_b128 v[92:95], v38 offset:5120
	ds_read_b128 v[96:99], v38 offset:6144
	ds_read_b128 v[100:103], v38 offset:7168
	s_waitcnt lgkmcnt(11)
	v_pk_fma_f32 v[8:9], v[56:57], v[42:43], v[8:9] op_sel_hi:[0,1,1]
	v_pk_fma_f32 v[10:11], v[56:57], v[40:41], v[10:11] op_sel_hi:[0,1,1]
	s_waitcnt lgkmcnt(9)
	v_pk_fma_f32 v[20:21], v[64:65], v[42:43], v[20:21] op_sel_hi:[0,1,1]
	v_pk_fma_f32 v[22:23], v[64:65], v[40:41], v[22:23] op_sel_hi:[0,1,1]
	s_waitcnt lgkmcnt(7)
	v_pk_fma_f32 v[12:13], v[72:73], v[42:43], v[12:13] op_sel_hi:[0,1,1]
	v_pk_fma_f32 v[14:15], v[72:73], v[40:41], v[14:15] op_sel_hi:[0,1,1]
	s_waitcnt lgkmcnt(5)
; #define LAS __attribute__((address_space(3)))
; __device__ void p_weights_prod(const Args& a, LAS unsigned char* lds) {
;     ...
;         for (int c0 = 0; c0 < 128; c0 += 4) {
;             f32x4 w4[4], m4[4];
; #pragma unroll
;             for (int r2 = 0; r2 < 4; ++r2) w4[r2] = *(const LAS f32x4*)(wt + (4 * rq + r2) * 128 + c0);
; #pragma unroll
;             for (int cc = 0; cc < 4; ++cc) m4[cc] = *(const LAS f32x4*)(mmt + (c0 + cc) * 256 + lc0);
; #pragma unroll
;             for (int r2 = 0; r2 < 4; ++r2)
; #pragma unroll
;                 for (int cc = 0; cc < 4; ++cc) acc[r2] += m4[cc] * w4[r2][cc];
;         }
	v_pk_fma_f32 v[16:17], v[42:43], v[80:81], v[16:17] op_sel_hi:[1,0,1]
	v_pk_fma_f32 v[18:19], v[40:41], v[80:81], v[18:19] op_sel_hi:[1,0,1]
	v_pk_fma_f32 v[8:9], v[56:57], v[46:47], v[8:9] op_sel:[1,0,0]
	v_pk_fma_f32 v[10:11], v[56:57], v[44:45], v[10:11] op_sel:[1,0,0]
	v_pk_fma_f32 v[20:21], v[64:65], v[46:47], v[20:21] op_sel:[1,0,0]
	v_pk_fma_f32 v[22:23], v[64:65], v[44:45], v[22:23] op_sel:[1,0,0]
	v_pk_fma_f32 v[12:13], v[72:73], v[46:47], v[12:13] op_sel:[1,0,0]
	v_pk_fma_f32 v[14:15], v[72:73], v[44:45], v[14:15] op_sel:[1,0,0]
	v_pk_fma_f32 v[16:17], v[80:81], v[46:47], v[16:17] op_sel:[1,0,0]
	v_pk_fma_f32 v[18:19], v[80:81], v[44:45], v[18:19] op_sel:[1,0,0]
	v_mov_b32_e32 v40, v59
	v_mov_b32_e32 v42, v67
	v_mov_b32_e32 v104, v75
	v_mov_b32_e32 v106, v83
	v_pk_fma_f32 v[10:11], v[58:59], v[48:49], v[10:11] op_sel_hi:[0,1,1]
	v_pk_fma_f32 v[8:9], v[58:59], v[50:51], v[8:9] op_sel_hi:[0,1,1]
	v_pk_fma_f32 v[22:23], v[66:67], v[48:49], v[22:23] op_sel_hi:[0,1,1]
	v_pk_fma_f32 v[20:21], v[66:67], v[50:51], v[20:21] op_sel_hi:[0,1,1]
	v_pk_fma_f32 v[14:15], v[74:75], v[48:49], v[14:15] op_sel_hi:[0,1,1]
	v_pk_fma_f32 v[12:13], v[74:75], v[50:51], v[12:13] op_sel_hi:[0,1,1]
	v_pk_fma_f32 v[18:19], v[82:83], v[48:49], v[18:19] op_sel_hi:[0,1,1]
	v_pk_fma_f32 v[16:17], v[82:83], v[50:51], v[16:17] op_sel_hi:[0,1,1]
	v_pk_fma_f32 v[8:9], v[40:41], v[54:55], v[8:9] op_sel_hi:[0,1,1]
	v_pk_fma_f32 v[10:11], v[40:41], v[52:53], v[10:11] op_sel_hi:[0,1,1]
	v_pk_fma_f32 v[20:21], v[42:43], v[54:55], v[20:21] op_sel_hi:[0,1,1]
	v_pk_fma_f32 v[22:23], v[42:43], v[52:53], v[22:23] op_sel_hi:[0,1,1]
	v_pk_fma_f32 v[12:13], v[104:105], v[54:55], v[12:13] op_sel_hi:[0,1,1]
	v_pk_fma_f32 v[14:15], v[104:105], v[52:53], v[14:15] op_sel_hi:[0,1,1]
	v_pk_fma_f32 v[16:17], v[106:107], v[54:55], v[16:17] op_sel_hi:[0,1,1]
	v_pk_fma_f32 v[18:19], v[106:107], v[52:53], v[18:19] op_sel_hi:[0,1,1]
	s_waitcnt lgkmcnt(3)
	v_pk_fma_f32 v[10:11], v[60:61], v[88:89], v[10:11] op_sel_hi:[0,1,1]
	v_pk_fma_f32 v[8:9], v[60:61], v[90:91], v[8:9] op_sel_hi:[0,1,1]
	v_pk_fma_f32 v[22:23], v[68:69], v[88:89], v[22:23] op_sel_hi:[0,1,1]
	v_pk_fma_f32 v[20:21], v[68:69], v[90:91], v[20:21] op_sel_hi:[0,1,1]
	v_pk_fma_f32 v[14:15], v[76:77], v[88:89], v[14:15] op_sel_hi:[0,1,1]
	v_pk_fma_f32 v[12:13], v[76:77], v[90:91], v[12:13] op_sel_hi:[0,1,1]
	v_pk_fma_f32 v[18:19], v[88:89], v[84:85], v[18:19] op_sel_hi:[1,0,1]
	v_pk_fma_f32 v[16:17], v[90:91], v[84:85], v[16:17] op_sel_hi:[1,0,1]
	s_waitcnt lgkmcnt(2)
	v_pk_fma_f32 v[8:9], v[60:61], v[94:95], v[8:9] op_sel:[1,0,0]
	v_pk_fma_f32 v[10:11], v[60:61], v[92:93], v[10:11] op_sel:[1,0,0]
	v_pk_fma_f32 v[20:21], v[68:69], v[94:95], v[20:21] op_sel:[1,0,0]
	v_pk_fma_f32 v[22:23], v[68:69], v[92:93], v[22:23] op_sel:[1,0,0]
	v_pk_fma_f32 v[12:13], v[76:77], v[94:95], v[12:13] op_sel:[1,0,0]
	v_pk_fma_f32 v[14:15], v[76:77], v[92:93], v[14:15] op_sel:[1,0,0]
	v_pk_fma_f32 v[16:17], v[84:85], v[94:95], v[16:17] op_sel:[1,0,0]
	v_pk_fma_f32 v[18:19], v[84:85], v[92:93], v[18:19] op_sel:[1,0,0]
	s_add_i32 s10, s10, 8
	v_mov_b32_e32 v108, v63
	v_mov_b32_e32 v110, v71
	v_mov_b32_e32 v112, v79
	v_mov_b32_e32 v114, v87
	s_waitcnt lgkmcnt(1)
	v_pk_fma_f32 v[10:11], v[62:63], v[96:97], v[10:11] op_sel_hi:[0,1,1]
	v_pk_fma_f32 v[8:9], v[62:63], v[98:99], v[8:9] op_sel_hi:[0,1,1]
	v_pk_fma_f32 v[22:23], v[70:71], v[96:97], v[22:23] op_sel_hi:[0,1,1]
	v_pk_fma_f32 v[20:21], v[70:71], v[98:99], v[20:21] op_sel_hi:[0,1,1]
	v_pk_fma_f32 v[14:15], v[78:79], v[96:97], v[14:15] op_sel_hi:[0,1,1]
	v_pk_fma_f32 v[12:13], v[78:79], v[98:99], v[12:13] op_sel_hi:[0,1,1]
	v_pk_fma_f32 v[18:19], v[86:87], v[96:97], v[18:19] op_sel_hi:[0,1,1]
	v_pk_fma_f32 v[16:17], v[86:87], v[98:99], v[16:17] op_sel_hi:[0,1,1]
	v_add_u32_e32 v38, 0x2000, v38
	v_add_u32_e32 v37, 32, v37
	s_cmpk_gt_u32 s10, 0x7b
	s_waitcnt lgkmcnt(0)
	v_pk_fma_f32 v[8:9], v[108:109], v[102:103], v[8:9] op_sel_hi:[0,1,1]
	v_pk_fma_f32 v[10:11], v[108:109], v[100:101], v[10:11] op_sel_hi:[0,1,1]
	v_pk_fma_f32 v[20:21], v[110:111], v[102:103], v[20:21] op_sel_hi:[0,1,1]
	v_pk_fma_f32 v[22:23], v[110:111], v[100:101], v[22:23] op_sel_hi:[0,1,1]
	v_pk_fma_f32 v[12:13], v[112:113], v[102:103], v[12:13] op_sel_hi:[0,1,1]
	v_pk_fma_f32 v[14:15], v[112:113], v[100:101], v[14:15] op_sel_hi:[0,1,1]
	v_pk_fma_f32 v[16:17], v[114:115], v[102:103], v[16:17] op_sel_hi:[0,1,1]
	v_pk_fma_f32 v[18:19], v[114:115], v[100:101], v[18:19] op_sel_hi:[0,1,1]
	s_cbranch_scc0 .Lpw_ka
; #define LAS __attribute__((address_space(3)))
; __device__ void p_weights_prod(const Args& a, LAS unsigned char* lds) {
;     ...
;     for (int u = blockIdx.x; u < 256; u += gridDim.x) {
;         const int l = u >> 7, g = (u >> 5) & 3, kblk = u & 31, pn = 7 + g;
;         __syncthreads();
;         {
;             const int rr = tid >> 4, c8 = (tid & 15) * 8;
;             const float* src = a.w_in + (size_t)l * DM * INW + (size_t)(kblk * 32 + rr) * INW + 1280 + g * 128 + c8;
;             const f32x4* msrc = (const f32x4*)(MM + (size_t)(l * 4 + g) * 128 * 256) + tid;
;             f32x4 mreg[16];
; #pragma unroll
;             for (int j = 0; j < 16; ++j) mreg[j] = msrc[j * NTHREADS];
;             *(LAS f32x4*)(wt + rr * 128 + c8) = *(const f32x4*)src; *(LAS f32x4*)(wt + rr * 128 + c8 + 4) = *(const f32x4*)(src + 4);
; #pragma unroll
;             for (int j = 0; j < 16; ++j) ((LAS f32x4*)mmt)[tid + j * NTHREADS] = mreg[j];
;         }
;         __syncthreads();
;         f32x4 acc[4];
; #pragma unroll
;         for (int r2 = 0; r2 < 4; ++r2) acc[r2] = (f32x4){0.f, 0.f, 0.f, 0.f};
;     ...
;         const int k0 = kblk * 32 + 4 * rq;
;         const f32x4 gn = *(const f32x4*)(a.norm_gain + l * DM + k0);
; #pragma unroll
;         for (int j = 0; j < 4; ++j) {
;             f16x4 o;
; #pragma unroll
;             for (int r2 = 0; r2 < 4; ++r2) o[r2] = (f16)(acc[r2][j] * gn[r2]);
;             *(f16x4*)(W1T + ((size_t)l * N1 + pn * 256 + rho0 + j) * 1024 + k0) = o;
;         }
	v_add_u32_e32 v42, s56, v27
	s_lshl_b32 s56, s55, 10
	s_ashr_i32 s57, s56, 31
	s_lshl_b64 s[56:57], s[56:57], 2
	s_add_u32 s56, s20, s56
	s_addc_u32 s57, s21, s57
	v_ashrrev_i32_e32 v43, 31, v42
	v_lshl_add_u64 v[38:39], v[42:43], 2, s[56:57]
	global_load_dwordx4 v[38:41], v[38:39], off
	s_lshl_b32 s54, s54, 8
	s_mul_hi_i32 s10, s55, 0xb00
	s_mulk_i32 s55, 0xb00
	s_addk_i32 s54, 0x700
	s_add_u32 s54, s55, s54
	s_addc_u32 s10, s10, 0
	v_mov_b32_e32 v44, v22
	v_mov_b32_e32 v45, v14
	v_mov_b32_e32 v14, v23
	v_mov_b32_e32 v22, v20
	v_mov_b32_e32 v23, v12
	v_mov_b32_e32 v12, v21
	v_lshl_add_u64 v[20:21], v[42:43], 1, s[6:7]
	v_or_b32_e32 v42, s54, v2
	v_mov_b32_e32 v43, s10
	v_lshlrev_b64 v[42:43], 11, v[42:43]
	v_lshl_add_u64 v[46:47], v[20:21], 0, v[42:43]
	v_or_b32_e32 v48, 0x800, v42
	v_mov_b32_e32 v49, v43
	v_or_b32_e32 v50, 0x1000, v42
	v_mov_b32_e32 v51, v43
	v_or_b32_e32 v42, 0x1800, v42
	v_lshl_add_u64 v[48:49], v[20:21], 0, v[48:49]
	v_lshl_add_u64 v[50:51], v[20:21], 0, v[50:51]
	v_lshl_add_u64 v[20:21], v[20:21], 0, v[42:43]
	s_add_i32 s53, s53, s9
	s_cmpk_gt_i32 s53, 0xff
	s_waitcnt vmcnt(0)
	v_mov_b32_e32 v42, v39
	v_mov_b32_e32 v43, v40
	v_fma_mixlo_f16 v37, v10, v38, 0
	v_fma_mixlo_f16 v39, v11, v38, 0
	v_fma_mixlo_f16 v40, v8, v38, 0
	v_fma_mixlo_f16 v38, v9, v38, 0
	v_pk_mul_f32 v[8:9], v[44:45], v[42:43]
	v_fma_mixlo_f16 v18, v18, v41, 0
	v_pk_mul_f32 v[10:11], v[14:15], v[42:43]
	v_pk_mul_f32 v[14:15], v[22:23], v[42:43]
	v_pk_mul_f32 v[12:13], v[12:13], v[42:43]
	v_cvt_pk_f16_f32 v9, v8, v9
	v_fma_mixlo_f16 v19, v19, v41, 0
	v_fma_mixlo_f16 v16, v16, v41, 0
	v_fma_mixlo_f16 v17, v17, v41, 0
	v_cvt_pk_f16_f32 v11, v10, v11
	v_cvt_pk_f16_f32 v14, v14, v15
	v_cvt_pk_f16_f32 v15, v12, v13
	v_pack_b32_f16 v8, v37, v9
	v_alignbit_b32 v9, v18, v9, 16
	v_pack_b32_f16 v10, v39, v11
	v_alignbit_b32 v11, v19, v11, 16
	v_pack_b32_f16 v12, v40, v14
	v_alignbit_b32 v13, v16, v14, 16
	v_pack_b32_f16 v14, v38, v15
	v_alignbit_b32 v15, v17, v15, 16
	global_store_dwordx2 v[46:47], v[8:9], off
	global_store_dwordx2 v[48:49], v[10:11], off
	global_store_dwordx2 v[50:51], v[12:13], off
	global_store_dwordx2 v[20:21], v[14:15], off
	v_add_u32_e32 v0, 0x100, v0
	v_mov_b32_e32 v8, v0
	v_lshlrev_b32_e32 v10, 4, v8
	s_load_dword s9, s[0:1], 0x60
	s_add_u32 s6, s40, 0x1fb00000
	v_lshlrev_b32_e32 v1, 1, v8
	v_and_b32_e32 v2, 0x90, v10
	s_movk_i32 s3, 0x6c
	v_lshlrev_b32_e32 v3, 3, v8
	v_ashrrev_i32_e32 v9, 31, v8
	s_addc_u32 s7, s41, 0
	v_and_or_b32 v2, v1, s3, v2
	v_ashrrev_i32_e32 v11, 6, v8
	v_ashrrev_i32_e32 v1, 4, v8
	v_and_b32_e32 v4, 0x78, v3
	v_lshl_add_u64 v[6:7], v[8:9], 4, s[40:41]
	s_mov_b64 s[4:5], 0x20a00000
	v_and_b32_e32 v8, 63, v8
	v_lshl_add_u64 v[6:7], v[6:7], 0, s[4:5]
	v_lshlrev_b32_e32 v3, 9, v1
	v_lshlrev_b32_e32 v9, 2, v4
	v_add_u32_e32 v24, 0, v10
	s_add_u32 s4, s0, 0x60
	v_lshl_add_u32 v8, v8, 4, 0
	v_mov_b32_e32 v5, 0
	s_mov_b32 s11, 0
	v_add3_u32 v3, 0, v3, v9
	s_movk_i32 s3, 0x4000
	v_add_u32_e32 v25, 0x4000, v24
	v_lshl_add_u32 v26, v11, 11, 0
	v_lshlrev_b32_e32 v27, 2, v11
	s_addc_u32 s5, s1, 0
	s_mov_b32 s14, 0x14000
	v_add_u32_e32 v28, 0x14000, v24
	s_mov_b32 s15, 0x16000
	v_add_u32_e32 v29, 0x16000, v24
	s_mov_b32 s33, 0x18000
	v_add_u32_e32 v30, 0x18000, v24
	s_mov_b32 s34, 0x1a000
	v_add_u32_e32 v31, 0x1a000, v24
	s_mov_b32 s35, 0x1c000
	v_add_u32_e32 v32, 0x1c000, v24
	s_mov_b32 s36, 0x1e000
	v_add_u32_e32 v33, 0x1e000, v24
	v_add_u32_e32 v34, 0x20000, v24
	v_add_u32_e32 v35, 0x22000, v24
	v_add_u32_e32 v36, 0x4000, v8
	s_movk_i32 s37, 0x2400
	s_movk_i32 s44, 0x2000
	s_movk_i32 s45, 0x6000
	s_mov_b32 s46, 0x8000
	s_mov_b32 s47, 0xa000
	s_mov_b32 s48, 0xc000
	s_mov_b32 s49, 0xe000
	s_mov_b32 s50, 0x10000
	s_mov_b32 s51, 0x12000
	v_lshlrev_b32_e32 v4, 2, v4
	s_mov_b64 s[12:13], 0x1400
	s_movk_i32 s52, 0x1000
	s_mov_b32 s53, s2
	s_ashr_i32 s55, s53, 7
	s_bfe_u32 s54, s53, 0x20005
	s_mul_i32 s56, s55, 0x900000
	s_mul_hi_i32 s10, s55, 0x900000
	s_add_u32 s58, s22, s56
	s_addc_u32 s59, s23, s10
	s_lshl_b32 s10, s53, 5
	s_and_b32 s56, s10, 0x3e0
	v_add_u32_e32 v10, s56, v1
	v_mov_b64_e32 v[8:9], s[58:59]
	v_mad_i64_i32 v[8:9], s[58:59], v10, s37, v[8:9]
	s_lshl_b32 s10, s54, 9
	v_lshl_add_u64 v[8:9], v[8:9], 0, s[10:11]
	s_lshl_b32 s10, s55, 2
	s_or_b32 s58, s10, s54
	v_lshl_add_u64 v[8:9], v[8:9], 0, v[4:5]
	s_ashr_i32 s59, s58, 31
	v_add_co_u32_e32 v10, vcc, s52, v8
	s_lshl_b64 s[58:59], s[58:59], 17
	s_nop 0
	v_addc_co_u32_e32 v11, vcc, 0, v9, vcc
	v_lshl_add_u64 v[86:87], v[6:7], 0, s[58:59]
	v_add_co_u32_e32 v20, vcc, s44, v86
	v_lshl_add_u64 v[12:13], v[8:9], 0, s[12:13]
	s_nop 0
	v_addc_co_u32_e32 v21, vcc, 0, v87, vcc
	v_add_co_u32_e32 v38, vcc, s3, v86
	s_waitcnt lgkmcnt(0)
	s_nop 0
	v_addc_co_u32_e32 v39, vcc, 0, v87, vcc
	v_add_co_u32_e32 v42, vcc, s45, v86
	s_nop 0
	v_addc_co_u32_e32 v43, vcc, 0, v87, vcc
	v_add_co_u32_e32 v46, vcc, s46, v86
	s_nop 1
	v_addc_co_u32_e32 v47, vcc, 0, v87, vcc
	v_add_co_u32_e32 v50, vcc, s47, v86
	s_nop 0
	v_addc_co_u32_e32 v51, vcc, 0, v87, vcc
	v_add_co_u32_e32 v54, vcc, s48, v86
	s_nop 0
	v_addc_co_u32_e32 v55, vcc, 0, v87, vcc
	v_add_co_u32_e32 v58, vcc, s49, v86
	s_nop 0
	v_addc_co_u32_e32 v59, vcc, 0, v87, vcc
	v_add_co_u32_e32 v62, vcc, s50, v86
	s_nop 0
	v_addc_co_u32_e32 v63, vcc, 0, v87, vcc
	v_add_co_u32_e32 v66, vcc, s51, v86
	s_mov_b32 s10, -4
	s_nop 0
	v_addc_co_u32_e32 v67, vcc, 0, v87, vcc
	v_add_co_u32_e32 v70, vcc, s14, v86
	v_mov_b32_e32 v37, v26
	s_nop 0
	v_addc_co_u32_e32 v71, vcc, 0, v87, vcc
	v_add_co_u32_e32 v74, vcc, s15, v86
	s_nop 1
	v_addc_co_u32_e32 v75, vcc, 0, v87, vcc
	v_add_co_u32_e32 v78, vcc, s33, v86
	s_nop 0
	s_nop 0
	s_nop 0
	s_nop 0
	s_nop 0
	v_addc_co_u32_e32 v79, vcc, 0, v87, vcc
	v_add_co_u32_e32 v82, vcc, s34, v86
	s_nop 1
	v_addc_co_u32_e32 v83, vcc, 0, v87, vcc
	v_add_co_u32_e32 v88, vcc, s35, v86
	s_nop 0
	v_addc_co_u32_e32 v89, vcc, 0, v87, vcc
	v_add_co_u32_e32 v90, vcc, s36, v86
	s_nop 1
	v_addc_co_u32_e32 v91, vcc, 0, v87, vcc
	s_nop 0
	s_waitcnt vmcnt(0)
	v_mov_b32_e32 v38, v36
	v_mov_b32_e32 v10, 0
	v_mov_b32_e32 v11, v5
	v_mov_b32_e32 v8, 0
	v_mov_b32_e32 v9, v5
	v_mov_b32_e32 v22, 0
	v_mov_b32_e32 v23, v5
	v_mov_b32_e32 v20, 0
	v_mov_b32_e32 v21, v5
	v_mov_b32_e32 v14, 0
	v_mov_b32_e32 v15, v5
	v_mov_b32_e32 v12, 0
	v_mov_b32_e32 v13, v5
	v_mov_b32_e32 v18, 0
	v_mov_b32_e32 v19, v5
	v_mov_b32_e32 v16, 0
	v_mov_b32_e32 v17, v5
; #define LAS __attribute__((address_space(3)))
; __device__ void p_weights_prod(const Args& a, LAS unsigned char* lds) {
;     ...
;         for (int c0 = 0; c0 < 128; c0 += 4) {
;             f32x4 w4[4], m4[4];
; #pragma unroll
;             for (int r2 = 0; r2 < 4; ++r2) w4[r2] = *(const LAS f32x4*)(wt + (4 * rq + r2) * 128 + c0);
; #pragma unroll
;             for (int cc = 0; cc < 4; ++cc) m4[cc] = *(const LAS f32x4*)(mmt + (c0 + cc) * 256 + lc0);
; #pragma unroll
;             for (int r2 = 0; r2 < 4; ++r2)
; #pragma unroll
;                 for (int cc = 0; cc < 4; ++cc) acc[r2] += m4[cc] * w4[r2][cc];
;         }
.Lpw_kb:
	ds_read_b128 v[40:43], v38
	ds_read_b128 v[44:47], v38 offset:1024
	ds_read_b128 v[48:51], v38 offset:2048
	ds_read_b128 v[52:55], v38 offset:3072
	ds_read_b128 v[56:59], v37
	ds_read_b128 v[60:63], v37 offset:16
	ds_read_b128 v[64:67], v37 offset:512
	ds_read_b128 v[68:71], v37 offset:528
	ds_read_b128 v[72:75], v37 offset:1024
	ds_read_b128 v[76:79], v37 offset:1040
	ds_read_b128 v[80:83], v37 offset:1536
	ds_read_b128 v[84:87], v37 offset:1552
	ds_read_b128 v[88:91], v38 offset:4096
	ds_read_b128 v[92:95], v38 offset:5120
	ds_read_b128 v[96:99], v38 offset:6144
	ds_read_b128 v[100:103], v38 offset:7168
	s_waitcnt lgkmcnt(11)
	v_pk_fma_f32 v[8:9], v[56:57], v[42:43], v[8:9] op_sel_hi:[0,1,1]
	v_pk_fma_f32 v[10:11], v[56:57], v[40:41], v[10:11] op_sel_hi:[0,1,1]
	s_waitcnt lgkmcnt(9)
	v_pk_fma_f32 v[20:21], v[64:65], v[42:43], v[20:21] op_sel_hi:[0,1,1]
	v_pk_fma_f32 v[22:23], v[64:65], v[40:41], v[22:23] op_sel_hi:[0,1,1]
	s_waitcnt lgkmcnt(7)
	v_pk_fma_f32 v[12:13], v[72:73], v[42:43], v[12:13] op_sel_hi:[0,1,1]
	v_pk_fma_f32 v[14:15], v[72:73], v[40:41], v[14:15] op_sel_hi:[0,1,1]
	s_waitcnt lgkmcnt(5)
	v_pk_fma_f32 v[16:17], v[42:43], v[80:81], v[16:17] op_sel_hi:[1,0,1]
	v_pk_fma_f32 v[18:19], v[40:41], v[80:81], v[18:19] op_sel_hi:[1,0,1]
	v_pk_fma_f32 v[8:9], v[56:57], v[46:47], v[8:9] op_sel:[1,0,0]
	v_pk_fma_f32 v[10:11], v[56:57], v[44:45], v[10:11] op_sel:[1,0,0]
	v_pk_fma_f32 v[20:21], v[64:65], v[46:47], v[20:21] op_sel:[1,0,0]
	v_pk_fma_f32 v[22:23], v[64:65], v[44:45], v[22:23] op_sel:[1,0,0]
	v_pk_fma_f32 v[12:13], v[72:73], v[46:47], v[12:13] op_sel:[1,0,0]
	v_pk_fma_f32 v[14:15], v[72:73], v[44:45], v[14:15] op_sel:[1,0,0]
	v_pk_fma_f32 v[16:17], v[80:81], v[46:47], v[16:17] op_sel:[1,0,0]
	v_pk_fma_f32 v[18:19], v[80:81], v[44:45], v[18:19] op_sel:[1,0,0]
	v_mov_b32_e32 v40, v59
	v_mov_b32_e32 v42, v67
	v_mov_b32_e32 v104, v75
	v_mov_b32_e32 v106, v83
	v_pk_fma_f32 v[10:11], v[58:59], v[48:49], v[10:11] op_sel_hi:[0,1,1]
	v_pk_fma_f32 v[8:9], v[58:59], v[50:51], v[8:9] op_sel_hi:[0,1,1]
	v_pk_fma_f32 v[22:23], v[66:67], v[48:49], v[22:23] op_sel_hi:[0,1,1]
	v_pk_fma_f32 v[20:21], v[66:67], v[50:51], v[20:21] op_sel_hi:[0,1,1]
	v_pk_fma_f32 v[14:15], v[74:75], v[48:49], v[14:15] op_sel_hi:[0,1,1]
	v_pk_fma_f32 v[12:13], v[74:75], v[50:51], v[12:13] op_sel_hi:[0,1,1]
	v_pk_fma_f32 v[18:19], v[82:83], v[48:49], v[18:19] op_sel_hi:[0,1,1]
	v_pk_fma_f32 v[16:17], v[82:83], v[50:51], v[16:17] op_sel_hi:[0,1,1]
	v_pk_fma_f32 v[8:9], v[40:41], v[54:55], v[8:9] op_sel_hi:[0,1,1]
	v_pk_fma_f32 v[10:11], v[40:41], v[52:53], v[10:11] op_sel_hi:[0,1,1]
	v_pk_fma_f32 v[20:21], v[42:43], v[54:55], v[20:21] op_sel_hi:[0,1,1]
	v_pk_fma_f32 v[22:23], v[42:43], v[52:53], v[22:23] op_sel_hi:[0,1,1]
	v_pk_fma_f32 v[12:13], v[104:105], v[54:55], v[12:13] op_sel_hi:[0,1,1]
	v_pk_fma_f32 v[14:15], v[104:105], v[52:53], v[14:15] op_sel_hi:[0,1,1]
	v_pk_fma_f32 v[16:17], v[106:107], v[54:55], v[16:17] op_sel_hi:[0,1,1]
	v_pk_fma_f32 v[18:19], v[106:107], v[52:53], v[18:19] op_sel_hi:[0,1,1]
	s_waitcnt lgkmcnt(3)
	v_pk_fma_f32 v[10:11], v[60:61], v[88:89], v[10:11] op_sel_hi:[0,1,1]
	v_pk_fma_f32 v[8:9], v[60:61], v[90:91], v[8:9] op_sel_hi:[0,1,1]
	v_pk_fma_f32 v[22:23], v[68:69], v[88:89], v[22:23] op_sel_hi:[0,1,1]
	v_pk_fma_f32 v[20:21], v[68:69], v[90:91], v[20:21] op_sel_hi:[0,1,1]
	v_pk_fma_f32 v[14:15], v[76:77], v[88:89], v[14:15] op_sel_hi:[0,1,1]
	v_pk_fma_f32 v[12:13], v[76:77], v[90:91], v[12:13] op_sel_hi:[0,1,1]
	v_pk_fma_f32 v[18:19], v[88:89], v[84:85], v[18:19] op_sel_hi:[1,0,1]
	v_pk_fma_f32 v[16:17], v[90:91], v[84:85], v[16:17] op_sel_hi:[1,0,1]
	s_waitcnt lgkmcnt(2)
	v_pk_fma_f32 v[8:9], v[60:61], v[94:95], v[8:9] op_sel:[1,0,0]
	v_pk_fma_f32 v[10:11], v[60:61], v[92:93], v[10:11] op_sel:[1,0,0]
	v_pk_fma_f32 v[20:21], v[68:69], v[94:95], v[20:21] op_sel:[1,0,0]
	v_pk_fma_f32 v[22:23], v[68:69], v[92:93], v[22:23] op_sel:[1,0,0]
	v_pk_fma_f32 v[12:13], v[76:77], v[94:95], v[12:13] op_sel:[1,0,0]
	v_pk_fma_f32 v[14:15], v[76:77], v[92:93], v[14:15] op_sel:[1,0,0]
	v_pk_fma_f32 v[16:17], v[84:85], v[94:95], v[16:17] op_sel:[1,0,0]
	v_pk_fma_f32 v[18:19], v[84:85], v[92:93], v[18:19] op_sel:[1,0,0]
	s_add_i32 s10, s10, 8
	v_mov_b32_e32 v108, v63
	v_mov_b32_e32 v110, v71
	v_mov_b32_e32 v112, v79
	v_mov_b32_e32 v114, v87
	s_waitcnt lgkmcnt(1)
	v_pk_fma_f32 v[10:11], v[62:63], v[96:97], v[10:11] op_sel_hi:[0,1,1]
	v_pk_fma_f32 v[8:9], v[62:63], v[98:99], v[8:9] op_sel_hi:[0,1,1]
	v_pk_fma_f32 v[22:23], v[70:71], v[96:97], v[22:23] op_sel_hi:[0,1,1]
	v_pk_fma_f32 v[20:21], v[70:71], v[98:99], v[20:21] op_sel_hi:[0,1,1]
	v_pk_fma_f32 v[14:15], v[78:79], v[96:97], v[14:15] op_sel_hi:[0,1,1]
	v_pk_fma_f32 v[12:13], v[78:79], v[98:99], v[12:13] op_sel_hi:[0,1,1]
	v_pk_fma_f32 v[18:19], v[86:87], v[96:97], v[18:19] op_sel_hi:[0,1,1]
	v_pk_fma_f32 v[16:17], v[86:87], v[98:99], v[16:17] op_sel_hi:[0,1,1]
	v_add_u32_e32 v38, 0x2000, v38
	v_add_u32_e32 v37, 32, v37
	s_cmpk_gt_u32 s10, 0x7b
	s_waitcnt lgkmcnt(0)
	v_pk_fma_f32 v[8:9], v[108:109], v[102:103], v[8:9] op_sel_hi:[0,1,1]
	v_pk_fma_f32 v[10:11], v[108:109], v[100:101], v[10:11] op_sel_hi:[0,1,1]
	v_pk_fma_f32 v[20:21], v[110:111], v[102:103], v[20:21] op_sel_hi:[0,1,1]
	v_pk_fma_f32 v[22:23], v[110:111], v[100:101], v[22:23] op_sel_hi:[0,1,1]
	v_pk_fma_f32 v[12:13], v[112:113], v[102:103], v[12:13] op_sel_hi:[0,1,1]
	v_pk_fma_f32 v[14:15], v[112:113], v[100:101], v[14:15] op_sel_hi:[0,1,1]
	v_pk_fma_f32 v[16:17], v[114:115], v[102:103], v[16:17] op_sel_hi:[0,1,1]
	v_pk_fma_f32 v[18:19], v[114:115], v[100:101], v[18:19] op_sel_hi:[0,1,1]
	s_cbranch_scc0 .Lpw_kb
; __device__ void p0_xconv(const Args& a) {
;     f16* XH = (f16*)(a.ws + WS_XH); float* SS = (float*)(a.ws + WS_SS);
;     int tid_ = threadIdx.x; asm volatile("" : "+v"(tid_));
;     const int lane = tid_ & 63, wv = tid_ >> 6;
;     const int nwv = (int)gridDim.x * 8;
;     for (int row0 = (int)blockIdx.x * 8 + wv; row0 < MROWS; row0 += 4 * nwv) {
;         f32x4 v[4][4];
; #pragma unroll
;         for (int r = 0; r < 4; ++r) {
;             const int row = row0 + r * nwv;
;             if (row < MROWS) {
;                 const float* src = (row < ROWS_PROMPT) ? a.x_prompt + (size_t)row * DM : a.x_sample + (size_t)(row - ROWS_PROMPT) * DM;
; #pragma unroll
;                 for (int i = 0; i < 4; ++i) v[r][i] = __builtin_nontemporal_load((const f32x4*)(src + i * 256 + lane * 4));
;             }
;         }
; __device__ void p_weights_prod(const Args& a, LAS unsigned char* lds) {
;     ...
;         const int k0 = kblk * 32 + 4 * rq;
;         const f32x4 gn = *(const f32x4*)(a.norm_gain + l * DM + k0);
; #pragma unroll
;         for (int j = 0; j < 4; ++j) {
;             f16x4 o;
; #pragma unroll
;             for (int r2 = 0; r2 < 4; ++r2) o[r2] = (f16)(acc[r2][j] * gn[r2]);
;             *(f16x4*)(W1T + ((size_t)l * N1 + pn * 256 + rho0 + j) * 1024 + k0) = o;
;         }
	v_add_u32_e32 v42, s56, v27
	s_lshl_b32 s56, s55, 10
	s_ashr_i32 s57, s56, 31
	s_lshl_b64 s[56:57], s[56:57], 2
	s_add_u32 s56, s20, s56
	s_addc_u32 s57, s21, s57
	v_ashrrev_i32_e32 v43, 31, v42
	v_lshl_add_u64 v[38:39], v[42:43], 2, s[56:57]
	global_load_dwordx4 v[38:41], v[38:39], off
	s_lshl_b32 s54, s54, 8
	s_mul_hi_i32 s10, s55, 0xb00
	s_mulk_i32 s55, 0xb00
	s_addk_i32 s54, 0x700
	s_add_u32 s54, s55, s54
	s_addc_u32 s10, s10, 0
	v_mov_b32_e32 v44, v22
	v_mov_b32_e32 v45, v14
	v_mov_b32_e32 v14, v23
	v_mov_b32_e32 v22, v20
	v_mov_b32_e32 v23, v12
	v_mov_b32_e32 v12, v21
	v_lshl_add_u64 v[20:21], v[42:43], 1, s[6:7]
	v_or_b32_e32 v42, s54, v2
	v_mov_b32_e32 v43, s10
	v_lshlrev_b64 v[42:43], 11, v[42:43]
	v_lshl_add_u64 v[46:47], v[20:21], 0, v[42:43]
	v_or_b32_e32 v48, 0x800, v42
	v_mov_b32_e32 v49, v43
	v_or_b32_e32 v50, 0x1000, v42
	v_mov_b32_e32 v51, v43
	v_or_b32_e32 v42, 0x1800, v42
	v_lshl_add_u64 v[48:49], v[20:21], 0, v[48:49]
	v_lshl_add_u64 v[50:51], v[20:21], 0, v[50:51]
	v_lshl_add_u64 v[20:21], v[20:21], 0, v[42:43]
	s_add_i32 s53, s53, s9
	s_cmpk_gt_i32 s53, 0xff
	s_waitcnt vmcnt(0)
	v_mov_b32_e32 v42, v39
	v_mov_b32_e32 v43, v40
	v_fma_mixlo_f16 v37, v10, v38, 0
	v_fma_mixlo_f16 v39, v11, v38, 0
	v_fma_mixlo_f16 v40, v8, v38, 0
	v_fma_mixlo_f16 v38, v9, v38, 0
	v_pk_mul_f32 v[8:9], v[44:45], v[42:43]
	v_fma_mixlo_f16 v18, v18, v41, 0
	v_pk_mul_f32 v[10:11], v[14:15], v[42:43]
	v_pk_mul_f32 v[14:15], v[22:23], v[42:43]
	v_pk_mul_f32 v[12:13], v[12:13], v[42:43]
	v_cvt_pk_f16_f32 v9, v8, v9
	v_fma_mixlo_f16 v19, v19, v41, 0
	v_fma_mixlo_f16 v16, v16, v41, 0
	v_fma_mixlo_f16 v17, v17, v41, 0
	v_cvt_pk_f16_f32 v11, v10, v11
	v_cvt_pk_f16_f32 v14, v14, v15
	v_cvt_pk_f16_f32 v15, v12, v13
	v_pack_b32_f16 v8, v37, v9
	v_alignbit_b32 v9, v18, v9, 16
	v_pack_b32_f16 v10, v39, v11
	v_alignbit_b32 v11, v19, v11, 16
	v_pack_b32_f16 v12, v40, v14
	v_alignbit_b32 v13, v16, v14, 16
	v_pack_b32_f16 v14, v38, v15
	v_alignbit_b32 v15, v17, v15, 16
	global_store_dwordx2 v[46:47], v[8:9], off
	global_store_dwordx2 v[48:49], v[10:11], off
	global_store_dwordx2 v[50:51], v[12:13], off
	global_store_dwordx2 v[20:21], v[14:15], off
	v_add_u32_e32 v0, 0xffffff00, v0
	s_barrier
	s_branch .LBB0_112
.Lpw_x:
	s_barrier
	v_and_b32_e32 v136, 63, v0
	v_lshrrev_b32_e32 v137, 6, v0
	s_nop 0
	v_readfirstlane_b32 s3, v137
	s_nop 3
	s_lshl_b32 s4, s2, 2
	s_add_i32 s3, s3, s4
	s_add_i32 s3, s3, -4
	s_mov_b64 s[12:13], 1
	v_xor_b32_e32 v130, 1, v136
	v_lshlrev_b32_e32 v130, 2, v130
	v_xor_b32_e32 v131, 2, v136
	v_lshlrev_b32_e32 v131, 2, v131
	v_xor_b32_e32 v132, 4, v136
	v_lshlrev_b32_e32 v132, 2, v132
	v_xor_b32_e32 v133, 8, v136
	v_lshlrev_b32_e32 v133, 2, v133
	v_xor_b32_e32 v134, 16, v136
	v_lshlrev_b32_e32 v134, 2, v134
	v_xor_b32_e32 v135, 32, v136
	v_lshlrev_b32_e32 v135, 2, v135
	v_lshlrev_b32_e32 v140, 4, v136
	v_lshlrev_b32_e32 v144, 3, v136
	v_lshlrev_b32_e32 v186, 2, v136
	v_lshlrev_b32_e32 v141, 4, v136
	v_add_u32_e32 v141, 0x400000, v141
	v_lshlrev_b32_e32 v145, 3, v136
	v_add_u32_e32 v145, 0x200000, v145
	v_lshlrev_b32_e32 v187, 2, v136
	v_add_u32_e32 v187, 0x10000, v187
	v_lshlrev_b32_e32 v142, 4, v136
	v_add_u32_e32 v142, 0x800000, v142
	v_lshlrev_b32_e32 v146, 3, v136
	v_add_u32_e32 v146, 0x400000, v146
	v_lshlrev_b32_e32 v188, 2, v136
	v_add_u32_e32 v188, 0x20000, v188
	v_lshlrev_b32_e32 v143, 4, v136
	v_add_u32_e32 v143, 0xc00000, v143
	v_lshlrev_b32_e32 v147, 3, v136
	v_add_u32_e32 v147, 0x600000, v147
	v_lshlrev_b32_e32 v189, 2, v136
	v_add_u32_e32 v189, 0x30000, v189
	s_add_i32 s6, s3, 0x4000
	s_lshl_b32 s6, s6, 12
	s_add_u32 s4, s18, s6
	s_addc_u32 s5, s19, 0
	global_load_dwordx4 v[2:5], v140, s[4:5] nt
	global_load_dwordx4 v[6:9], v140, s[4:5] offset:1024 nt
	global_load_dwordx4 v[10:13], v140, s[4:5] offset:2048 nt
	global_load_dwordx4 v[14:17], v140, s[4:5] offset:3072 nt
	global_load_dwordx4 v[18:21], v141, s[4:5] nt
	global_load_dwordx4 v[22:25], v141, s[4:5] offset:1024 nt
	global_load_dwordx4 v[26:29], v141, s[4:5] offset:2048 nt
	global_load_dwordx4 v[30:33], v141, s[4:5] offset:3072 nt
	global_load_dwordx4 v[34:37], v142, s[4:5] nt
	global_load_dwordx4 v[38:41], v142, s[4:5] offset:1024 nt
	global_load_dwordx4 v[42:45], v142, s[4:5] offset:2048 nt
	global_load_dwordx4 v[46:49], v142, s[4:5] offset:3072 nt
	global_load_dwordx4 v[50:53], v143, s[4:5] nt
	global_load_dwordx4 v[54:57], v143, s[4:5] offset:1024 nt
	global_load_dwordx4 v[58:61], v143, s[4:5] offset:2048 nt
	global_load_dwordx4 v[62:65], v143, s[4:5] offset:3072 nt
	s_add_i32 s6, s3, 0x5000
	s_lshl_b32 s6, s6, 12
	s_add_u32 s4, s18, s6
	s_addc_u32 s5, s19, 0
	global_load_dwordx4 v[66:69], v140, s[4:5] nt
	global_load_dwordx4 v[70:73], v140, s[4:5] offset:1024 nt
	global_load_dwordx4 v[74:77], v140, s[4:5] offset:2048 nt
	global_load_dwordx4 v[78:81], v140, s[4:5] offset:3072 nt
	global_load_dwordx4 v[82:85], v141, s[4:5] nt
	global_load_dwordx4 v[86:89], v141, s[4:5] offset:1024 nt
	global_load_dwordx4 v[90:93], v141, s[4:5] offset:2048 nt
	global_load_dwordx4 v[94:97], v141, s[4:5] offset:3072 nt
	global_load_dwordx4 v[98:101], v142, s[4:5] nt
	global_load_dwordx4 v[102:105], v142, s[4:5] offset:1024 nt
	global_load_dwordx4 v[106:109], v142, s[4:5] offset:2048 nt
	global_load_dwordx4 v[110:113], v142, s[4:5] offset:3072 nt
	global_load_dwordx4 v[114:117], v143, s[4:5] nt
	global_load_dwordx4 v[118:121], v143, s[4:5] offset:1024 nt
	global_load_dwordx4 v[122:125], v143, s[4:5] offset:2048 nt
	global_load_dwordx4 v[126:129], v143, s[4:5] offset:3072 nt
	s_waitcnt vmcnt(16)
; __device__ void p0_xconv(const Args& a) {
;     ...
; #pragma unroll
;         for (int r = 0; r < 4; ++r) {
;             const int row = row0 + r * nwv;
;             if (row < MROWS) {
;                 float ss = 0.f;
; #pragma unroll
;                 for (int i = 0; i < 4; ++i) {
;                     const f32x4 x = v[r][i];
;                     ss += (x[0] * x[0] + x[1] * x[1]) + (x[2] * x[2] + x[3] * x[3]);
;                     f16x4 h; h[0] = (f16)x[0]; h[1] = (f16)x[1]; h[2] = (f16)x[2]; h[3] = (f16)x[3];
;                     *(f16x4*)(XH + (size_t)row * DM + i * 256 + lane * 4) = h;
;                 }
	s_add_i32 s6, s3, 0x8000
	s_lshl_b32 s7, s6, 11
	s_add_u32 s10, s40, s7
	s_addc_u32 s11, s41, 0
	s_lshl_b32 s7, s6, 6
	s_add_u32 s6, s40, s7
	s_addc_u32 s7, s41, 0
	s_add_u32 s6, s6, 0x1f800000
	s_addc_u32 s7, s7, 0
	v_mul_f32_e32 v150, v3, v3
	v_mul_f32_e32 v151, v5, v5
	v_fmac_f32_e32 v150, v2, v2
	v_fmac_f32_e32 v151, v4, v4
	v_add_f32_e32 v160, v150, v151
	v_cvt_pk_f16_f32 v170, v2, v3
	v_cvt_pk_f16_f32 v171, v4, v5
	v_mul_f32_e32 v150, v7, v7
	v_mul_f32_e32 v151, v9, v9
	v_fmac_f32_e32 v150, v6, v6
	v_fmac_f32_e32 v151, v8, v8
	v_add_f32_e32 v152, v150, v151
	v_add_f32_e32 v160, v160, v152
	v_cvt_pk_f16_f32 v172, v6, v7
	v_cvt_pk_f16_f32 v173, v8, v9
	v_mul_f32_e32 v150, v11, v11
	v_mul_f32_e32 v151, v13, v13
	v_fmac_f32_e32 v150, v10, v10
	v_fmac_f32_e32 v151, v12, v12
	v_add_f32_e32 v152, v150, v151
	v_add_f32_e32 v160, v160, v152
	v_cvt_pk_f16_f32 v174, v10, v11
	v_cvt_pk_f16_f32 v175, v12, v13
	v_mul_f32_e32 v150, v15, v15
	v_mul_f32_e32 v151, v17, v17
	v_fmac_f32_e32 v150, v14, v14
	v_fmac_f32_e32 v151, v16, v16
	v_add_f32_e32 v152, v150, v151
	v_add_f32_e32 v160, v160, v152
	v_cvt_pk_f16_f32 v176, v14, v15
	v_cvt_pk_f16_f32 v177, v16, v17
	global_store_dwordx2 v144, v[170:171], s[10:11]
	global_store_dwordx2 v144, v[172:173], s[10:11] offset:512
	global_store_dwordx2 v144, v[174:175], s[10:11] offset:1024
	global_store_dwordx2 v144, v[176:177], s[10:11] offset:1536
	v_mul_f32_e32 v150, v19, v19
	v_mul_f32_e32 v151, v21, v21
	v_fmac_f32_e32 v150, v18, v18
	v_fmac_f32_e32 v151, v20, v20
	v_add_f32_e32 v161, v150, v151
	v_cvt_pk_f16_f32 v178, v18, v19
	v_cvt_pk_f16_f32 v179, v20, v21
	v_mul_f32_e32 v150, v23, v23
	v_mul_f32_e32 v151, v25, v25
	v_fmac_f32_e32 v150, v22, v22
	v_fmac_f32_e32 v151, v24, v24
	v_add_f32_e32 v152, v150, v151
	v_add_f32_e32 v161, v161, v152
	v_cvt_pk_f16_f32 v180, v22, v23
	v_cvt_pk_f16_f32 v181, v24, v25
	v_mul_f32_e32 v150, v27, v27
	v_mul_f32_e32 v151, v29, v29
	v_fmac_f32_e32 v150, v26, v26
	v_fmac_f32_e32 v151, v28, v28
	v_add_f32_e32 v152, v150, v151
	v_add_f32_e32 v161, v161, v152
	v_cvt_pk_f16_f32 v182, v26, v27
	v_cvt_pk_f16_f32 v183, v28, v29
	v_mul_f32_e32 v150, v31, v31
	v_mul_f32_e32 v151, v33, v33
	v_fmac_f32_e32 v150, v30, v30
	v_fmac_f32_e32 v151, v32, v32
	v_add_f32_e32 v152, v150, v151
	v_add_f32_e32 v161, v161, v152
	v_cvt_pk_f16_f32 v184, v30, v31
	v_cvt_pk_f16_f32 v185, v32, v33
	global_store_dwordx2 v145, v[178:179], s[10:11]
	global_store_dwordx2 v145, v[180:181], s[10:11] offset:512
	global_store_dwordx2 v145, v[182:183], s[10:11] offset:1024
	global_store_dwordx2 v145, v[184:185], s[10:11] offset:1536
	v_mul_f32_e32 v150, v35, v35
	v_mul_f32_e32 v151, v37, v37
	v_fmac_f32_e32 v150, v34, v34
	v_fmac_f32_e32 v151, v36, v36
	v_add_f32_e32 v162, v150, v151
	v_cvt_pk_f16_f32 v170, v34, v35
	v_cvt_pk_f16_f32 v171, v36, v37
	v_mul_f32_e32 v150, v39, v39
	v_mul_f32_e32 v151, v41, v41
	v_fmac_f32_e32 v150, v38, v38
	v_fmac_f32_e32 v151, v40, v40
	v_add_f32_e32 v152, v150, v151
	v_add_f32_e32 v162, v162, v152
	v_cvt_pk_f16_f32 v172, v38, v39
	v_cvt_pk_f16_f32 v173, v40, v41
	v_mul_f32_e32 v150, v43, v43
	v_mul_f32_e32 v151, v45, v45
	v_fmac_f32_e32 v150, v42, v42
	v_fmac_f32_e32 v151, v44, v44
	v_add_f32_e32 v152, v150, v151
	v_add_f32_e32 v162, v162, v152
	v_cvt_pk_f16_f32 v174, v42, v43
	v_cvt_pk_f16_f32 v175, v44, v45
	v_mul_f32_e32 v150, v47, v47
	v_mul_f32_e32 v151, v49, v49
	v_fmac_f32_e32 v150, v46, v46
	v_fmac_f32_e32 v151, v48, v48
	v_add_f32_e32 v152, v150, v151
	v_add_f32_e32 v162, v162, v152
	v_cvt_pk_f16_f32 v176, v46, v47
	v_cvt_pk_f16_f32 v177, v48, v49
	global_store_dwordx2 v146, v[170:171], s[10:11]
	global_store_dwordx2 v146, v[172:173], s[10:11] offset:512
	global_store_dwordx2 v146, v[174:175], s[10:11] offset:1024
	global_store_dwordx2 v146, v[176:177], s[10:11] offset:1536
	v_mul_f32_e32 v150, v51, v51
	v_mul_f32_e32 v151, v53, v53
	v_fmac_f32_e32 v150, v50, v50
	v_fmac_f32_e32 v151, v52, v52
	v_add_f32_e32 v163, v150, v151
	v_cvt_pk_f16_f32 v178, v50, v51
	v_cvt_pk_f16_f32 v179, v52, v53
	v_mul_f32_e32 v150, v55, v55
	v_mul_f32_e32 v151, v57, v57
	v_fmac_f32_e32 v150, v54, v54
	v_fmac_f32_e32 v151, v56, v56
	v_add_f32_e32 v152, v150, v151
	v_add_f32_e32 v163, v163, v152
	v_cvt_pk_f16_f32 v180, v54, v55
	v_cvt_pk_f16_f32 v181, v56, v57
	v_mul_f32_e32 v150, v59, v59
	v_mul_f32_e32 v151, v61, v61
	v_fmac_f32_e32 v150, v58, v58
	v_fmac_f32_e32 v151, v60, v60
	v_add_f32_e32 v152, v150, v151
	v_add_f32_e32 v163, v163, v152
	v_cvt_pk_f16_f32 v182, v58, v59
	v_cvt_pk_f16_f32 v183, v60, v61
	v_mul_f32_e32 v150, v63, v63
	v_mul_f32_e32 v151, v65, v65
	v_fmac_f32_e32 v150, v62, v62
	v_fmac_f32_e32 v151, v64, v64
	v_add_f32_e32 v152, v150, v151
	v_add_f32_e32 v163, v163, v152
	v_cvt_pk_f16_f32 v184, v62, v63
	v_cvt_pk_f16_f32 v185, v64, v65
	global_store_dwordx2 v147, v[178:179], s[10:11]
	global_store_dwordx2 v147, v[180:181], s[10:11] offset:512
	global_store_dwordx2 v147, v[182:183], s[10:11] offset:1024
	global_store_dwordx2 v147, v[184:185], s[10:11] offset:1536
	ds_bpermute_b32 v164, v130, v160
	ds_bpermute_b32 v165, v130, v161
	ds_bpermute_b32 v166, v130, v162
	ds_bpermute_b32 v167, v130, v163
	s_waitcnt lgkmcnt(0)
	v_add_f32_e32 v160, v160, v164
	v_add_f32_e32 v161, v161, v165
	v_add_f32_e32 v162, v162, v166
	v_add_f32_e32 v163, v163, v167
	ds_bpermute_b32 v164, v131, v160
	ds_bpermute_b32 v165, v131, v161
	ds_bpermute_b32 v166, v131, v162
	ds_bpermute_b32 v167, v131, v163
	s_waitcnt lgkmcnt(0)
	v_add_f32_e32 v160, v160, v164
	v_add_f32_e32 v161, v161, v165
	v_add_f32_e32 v162, v162, v166
	v_add_f32_e32 v163, v163, v167
	ds_bpermute_b32 v164, v132, v160
	ds_bpermute_b32 v165, v132, v161
	ds_bpermute_b32 v166, v132, v162
	ds_bpermute_b32 v167, v132, v163
	s_waitcnt lgkmcnt(0)
; __device__ void p0_xconv(const Args& a) {
;     ...
;     for (int row0 = (int)blockIdx.x * 8 + wv; row0 < MROWS; row0 += 4 * nwv) {
;         f32x4 v[4][4];
; #pragma unroll
;         for (int r = 0; r < 4; ++r) {
;             const int row = row0 + r * nwv;
;             if (row < MROWS) {
;                 const float* src = (row < ROWS_PROMPT) ? a.x_prompt + (size_t)row * DM : a.x_sample + (size_t)(row - ROWS_PROMPT) * DM;
; #pragma unroll
;                 for (int i = 0; i < 4; ++i) v[r][i] = __builtin_nontemporal_load((const f32x4*)(src + i * 256 + lane * 4));
;             }
;         }
; #pragma unroll
;         for (int r = 0; r < 4; ++r) {
;             const int row = row0 + r * nwv;
;             if (row < MROWS) {
;                 float ss = 0.f;
; #pragma unroll
;                 for (int i = 0; i < 4; ++i) {
;                     const f32x4 x = v[r][i];
;                     ss += (x[0] * x[0] + x[1] * x[1]) + (x[2] * x[2] + x[3] * x[3]);
;                     f16x4 h; h[0] = (f16)x[0]; h[1] = (f16)x[1]; h[2] = (f16)x[2]; h[3] = (f16)x[3];
;                     *(f16x4*)(XH + (size_t)row * DM + i * 256 + lane * 4) = h;
;                 }
;     ...
;                 for (int o = 1; o < 64; o <<= 1) ss += __shfl_xor(ss, o);
;                 if (lane < 16) SS[(size_t)row * 16 + lane] = (lane == 0) ? ss : 0.f;
	v_add_f32_e32 v160, v160, v164
	v_add_f32_e32 v161, v161, v165
	v_add_f32_e32 v162, v162, v166
	v_add_f32_e32 v163, v163, v167
	ds_bpermute_b32 v164, v133, v160
	ds_bpermute_b32 v165, v133, v161
	ds_bpermute_b32 v166, v133, v162
	ds_bpermute_b32 v167, v133, v163
	s_waitcnt lgkmcnt(0)
	v_add_f32_e32 v160, v160, v164
	v_add_f32_e32 v161, v161, v165
	v_add_f32_e32 v162, v162, v166
	v_add_f32_e32 v163, v163, v167
	ds_bpermute_b32 v164, v134, v160
	ds_bpermute_b32 v165, v134, v161
	ds_bpermute_b32 v166, v134, v162
	ds_bpermute_b32 v167, v134, v163
	s_waitcnt lgkmcnt(0)
	v_add_f32_e32 v160, v160, v164
	v_add_f32_e32 v161, v161, v165
	v_add_f32_e32 v162, v162, v166
	v_add_f32_e32 v163, v163, v167
	ds_bpermute_b32 v164, v135, v160
	ds_bpermute_b32 v165, v135, v161
	ds_bpermute_b32 v166, v135, v162
	ds_bpermute_b32 v167, v135, v163
	s_waitcnt lgkmcnt(0)
	v_add_f32_e32 v160, v160, v164
	v_add_f32_e32 v161, v161, v165
	v_add_f32_e32 v162, v162, v166
	v_add_f32_e32 v163, v163, v167
	v_cndmask_b32_e64 v164, 0, v160, s[12:13]
	v_cndmask_b32_e64 v165, 0, v161, s[12:13]
	v_cndmask_b32_e64 v166, 0, v162, s[12:13]
	v_cndmask_b32_e64 v167, 0, v163, s[12:13]
	s_mov_b64 exec, 0xffff
	global_store_dword v186, v164, s[6:7]
	global_store_dword v187, v165, s[6:7]
	global_store_dword v188, v166, s[6:7]
	global_store_dword v189, v167, s[6:7]
	s_mov_b64 exec, -1
	s_barrier
	s_add_i32 s6, s3, 0x6000
	s_lshl_b32 s6, s6, 12
	s_add_u32 s4, s18, s6
	s_addc_u32 s5, s19, 0
	global_load_dwordx4 v[2:5], v140, s[4:5] nt
	global_load_dwordx4 v[6:9], v140, s[4:5] offset:1024 nt
	global_load_dwordx4 v[10:13], v140, s[4:5] offset:2048 nt
	global_load_dwordx4 v[14:17], v140, s[4:5] offset:3072 nt
	global_load_dwordx4 v[18:21], v141, s[4:5] nt
	global_load_dwordx4 v[22:25], v141, s[4:5] offset:1024 nt
	global_load_dwordx4 v[26:29], v141, s[4:5] offset:2048 nt
	global_load_dwordx4 v[30:33], v141, s[4:5] offset:3072 nt
	global_load_dwordx4 v[34:37], v142, s[4:5] nt
	global_load_dwordx4 v[38:41], v142, s[4:5] offset:1024 nt
	global_load_dwordx4 v[42:45], v142, s[4:5] offset:2048 nt
	global_load_dwordx4 v[46:49], v142, s[4:5] offset:3072 nt
	global_load_dwordx4 v[50:53], v143, s[4:5] nt
	global_load_dwordx4 v[54:57], v143, s[4:5] offset:1024 nt
	global_load_dwordx4 v[58:61], v143, s[4:5] offset:2048 nt
	global_load_dwordx4 v[62:65], v143, s[4:5] offset:3072 nt
	s_waitcnt vmcnt(36)
	s_add_i32 s6, s3, 0x9000
	s_lshl_b32 s7, s6, 11
	s_add_u32 s10, s40, s7
	s_addc_u32 s11, s41, 0
	s_lshl_b32 s7, s6, 6
	s_add_u32 s6, s40, s7
	s_addc_u32 s7, s41, 0
	s_add_u32 s6, s6, 0x1f800000
	s_addc_u32 s7, s7, 0
	v_mul_f32_e32 v150, v67, v67
	v_mul_f32_e32 v151, v69, v69
	v_fmac_f32_e32 v150, v66, v66
	v_fmac_f32_e32 v151, v68, v68
	v_add_f32_e32 v160, v150, v151
	v_cvt_pk_f16_f32 v170, v66, v67
	v_cvt_pk_f16_f32 v171, v68, v69
	v_mul_f32_e32 v150, v71, v71
	v_mul_f32_e32 v151, v73, v73
	v_fmac_f32_e32 v150, v70, v70
	v_fmac_f32_e32 v151, v72, v72
	v_add_f32_e32 v152, v150, v151
	v_add_f32_e32 v160, v160, v152
	v_cvt_pk_f16_f32 v172, v70, v71
	v_cvt_pk_f16_f32 v173, v72, v73
	v_mul_f32_e32 v150, v75, v75
	v_mul_f32_e32 v151, v77, v77
	v_fmac_f32_e32 v150, v74, v74
	v_fmac_f32_e32 v151, v76, v76
	v_add_f32_e32 v152, v150, v151
	v_add_f32_e32 v160, v160, v152
	v_cvt_pk_f16_f32 v174, v74, v75
	v_cvt_pk_f16_f32 v175, v76, v77
	v_mul_f32_e32 v150, v79, v79
	v_mul_f32_e32 v151, v81, v81
	v_fmac_f32_e32 v150, v78, v78
	v_fmac_f32_e32 v151, v80, v80
	v_add_f32_e32 v152, v150, v151
	v_add_f32_e32 v160, v160, v152
	v_cvt_pk_f16_f32 v176, v78, v79
	v_cvt_pk_f16_f32 v177, v80, v81
	global_store_dwordx2 v144, v[170:171], s[10:11]
	global_store_dwordx2 v144, v[172:173], s[10:11] offset:512
	global_store_dwordx2 v144, v[174:175], s[10:11] offset:1024
	global_store_dwordx2 v144, v[176:177], s[10:11] offset:1536
	v_mul_f32_e32 v150, v83, v83
	v_mul_f32_e32 v151, v85, v85
	v_fmac_f32_e32 v150, v82, v82
	v_fmac_f32_e32 v151, v84, v84
	v_add_f32_e32 v161, v150, v151
	v_cvt_pk_f16_f32 v178, v82, v83
	v_cvt_pk_f16_f32 v179, v84, v85
	v_mul_f32_e32 v150, v87, v87
	v_mul_f32_e32 v151, v89, v89
	v_fmac_f32_e32 v150, v86, v86
	v_fmac_f32_e32 v151, v88, v88
	v_add_f32_e32 v152, v150, v151
	v_add_f32_e32 v161, v161, v152
	v_cvt_pk_f16_f32 v180, v86, v87
	v_cvt_pk_f16_f32 v181, v88, v89
	v_mul_f32_e32 v150, v91, v91
	v_mul_f32_e32 v151, v93, v93
	v_fmac_f32_e32 v150, v90, v90
	v_fmac_f32_e32 v151, v92, v92
	v_add_f32_e32 v152, v150, v151
	v_add_f32_e32 v161, v161, v152
	v_cvt_pk_f16_f32 v182, v90, v91
	v_cvt_pk_f16_f32 v183, v92, v93
	v_mul_f32_e32 v150, v95, v95
	v_mul_f32_e32 v151, v97, v97
	v_fmac_f32_e32 v150, v94, v94
	v_fmac_f32_e32 v151, v96, v96
	v_add_f32_e32 v152, v150, v151
	v_add_f32_e32 v161, v161, v152
	v_cvt_pk_f16_f32 v184, v94, v95
	v_cvt_pk_f16_f32 v185, v96, v97
	global_store_dwordx2 v145, v[178:179], s[10:11]
	global_store_dwordx2 v145, v[180:181], s[10:11] offset:512
	global_store_dwordx2 v145, v[182:183], s[10:11] offset:1024
	global_store_dwordx2 v145, v[184:185], s[10:11] offset:1536
	v_mul_f32_e32 v150, v99, v99
	v_mul_f32_e32 v151, v101, v101
	v_fmac_f32_e32 v150, v98, v98
	v_fmac_f32_e32 v151, v100, v100
	v_add_f32_e32 v162, v150, v151
	v_cvt_pk_f16_f32 v170, v98, v99
	v_cvt_pk_f16_f32 v171, v100, v101
	v_mul_f32_e32 v150, v103, v103
	v_mul_f32_e32 v151, v105, v105
	v_fmac_f32_e32 v150, v102, v102
	v_fmac_f32_e32 v151, v104, v104
	v_add_f32_e32 v152, v150, v151
	v_add_f32_e32 v162, v162, v152
	v_cvt_pk_f16_f32 v172, v102, v103
	v_cvt_pk_f16_f32 v173, v104, v105
	v_mul_f32_e32 v150, v107, v107
	v_mul_f32_e32 v151, v109, v109
	v_fmac_f32_e32 v150, v106, v106
	v_fmac_f32_e32 v151, v108, v108
; __device__ void p0_xconv(const Args& a) {
;     ...
;                 float ss = 0.f;
; #pragma unroll
;                 for (int i = 0; i < 4; ++i) {
;                     const f32x4 x = v[r][i];
;                     ss += (x[0] * x[0] + x[1] * x[1]) + (x[2] * x[2] + x[3] * x[3]);
;                     f16x4 h; h[0] = (f16)x[0]; h[1] = (f16)x[1]; h[2] = (f16)x[2]; h[3] = (f16)x[3];
;                     *(f16x4*)(XH + (size_t)row * DM + i * 256 + lane * 4) = h;
;                 }
; #pragma unroll
;                 for (int o = 1; o < 64; o <<= 1) ss += __shfl_xor(ss, o);
;                 if (lane < 16) SS[(size_t)row * 16 + lane] = (lane == 0) ? ss : 0.f;
	v_add_f32_e32 v152, v150, v151
	v_add_f32_e32 v162, v162, v152
	v_cvt_pk_f16_f32 v174, v106, v107
	v_cvt_pk_f16_f32 v175, v108, v109
	v_mul_f32_e32 v150, v111, v111
	v_mul_f32_e32 v151, v113, v113
	v_fmac_f32_e32 v150, v110, v110
	v_fmac_f32_e32 v151, v112, v112
	v_add_f32_e32 v152, v150, v151
	v_add_f32_e32 v162, v162, v152
	v_cvt_pk_f16_f32 v176, v110, v111
	v_cvt_pk_f16_f32 v177, v112, v113
	global_store_dwordx2 v146, v[170:171], s[10:11]
	global_store_dwordx2 v146, v[172:173], s[10:11] offset:512
	global_store_dwordx2 v146, v[174:175], s[10:11] offset:1024
	global_store_dwordx2 v146, v[176:177], s[10:11] offset:1536
	v_mul_f32_e32 v150, v115, v115
	v_mul_f32_e32 v151, v117, v117
	v_fmac_f32_e32 v150, v114, v114
	v_fmac_f32_e32 v151, v116, v116
	v_add_f32_e32 v163, v150, v151
	v_cvt_pk_f16_f32 v178, v114, v115
	v_cvt_pk_f16_f32 v179, v116, v117
	v_mul_f32_e32 v150, v119, v119
	v_mul_f32_e32 v151, v121, v121
	v_fmac_f32_e32 v150, v118, v118
	v_fmac_f32_e32 v151, v120, v120
	v_add_f32_e32 v152, v150, v151
	v_add_f32_e32 v163, v163, v152
	v_cvt_pk_f16_f32 v180, v118, v119
	v_cvt_pk_f16_f32 v181, v120, v121
	v_mul_f32_e32 v150, v123, v123
	v_mul_f32_e32 v151, v125, v125
	v_fmac_f32_e32 v150, v122, v122
	v_fmac_f32_e32 v151, v124, v124
	v_add_f32_e32 v152, v150, v151
	v_add_f32_e32 v163, v163, v152
	v_cvt_pk_f16_f32 v182, v122, v123
	v_cvt_pk_f16_f32 v183, v124, v125
	v_mul_f32_e32 v150, v127, v127
	v_mul_f32_e32 v151, v129, v129
	v_fmac_f32_e32 v150, v126, v126
	v_fmac_f32_e32 v151, v128, v128
	v_add_f32_e32 v152, v150, v151
	v_add_f32_e32 v163, v163, v152
	v_cvt_pk_f16_f32 v184, v126, v127
	v_cvt_pk_f16_f32 v185, v128, v129
	global_store_dwordx2 v147, v[178:179], s[10:11]
	global_store_dwordx2 v147, v[180:181], s[10:11] offset:512
	global_store_dwordx2 v147, v[182:183], s[10:11] offset:1024
	global_store_dwordx2 v147, v[184:185], s[10:11] offset:1536
	ds_bpermute_b32 v164, v130, v160
	ds_bpermute_b32 v165, v130, v161
	ds_bpermute_b32 v166, v130, v162
	ds_bpermute_b32 v167, v130, v163
	s_waitcnt lgkmcnt(0)
	v_add_f32_e32 v160, v160, v164
	v_add_f32_e32 v161, v161, v165
	v_add_f32_e32 v162, v162, v166
	v_add_f32_e32 v163, v163, v167
	ds_bpermute_b32 v164, v131, v160
	ds_bpermute_b32 v165, v131, v161
	ds_bpermute_b32 v166, v131, v162
	ds_bpermute_b32 v167, v131, v163
	s_waitcnt lgkmcnt(0)
	v_add_f32_e32 v160, v160, v164
	v_add_f32_e32 v161, v161, v165
	v_add_f32_e32 v162, v162, v166
	v_add_f32_e32 v163, v163, v167
	ds_bpermute_b32 v164, v132, v160
	ds_bpermute_b32 v165, v132, v161
	ds_bpermute_b32 v166, v132, v162
	ds_bpermute_b32 v167, v132, v163
	s_waitcnt lgkmcnt(0)
	v_add_f32_e32 v160, v160, v164
	v_add_f32_e32 v161, v161, v165
	v_add_f32_e32 v162, v162, v166
	v_add_f32_e32 v163, v163, v167
	ds_bpermute_b32 v164, v133, v160
	ds_bpermute_b32 v165, v133, v161
	ds_bpermute_b32 v166, v133, v162
	ds_bpermute_b32 v167, v133, v163
	s_waitcnt lgkmcnt(0)
	v_add_f32_e32 v160, v160, v164
	v_add_f32_e32 v161, v161, v165
	v_add_f32_e32 v162, v162, v166
	v_add_f32_e32 v163, v163, v167
	ds_bpermute_b32 v164, v134, v160
	ds_bpermute_b32 v165, v134, v161
	ds_bpermute_b32 v166, v134, v162
	ds_bpermute_b32 v167, v134, v163
	s_waitcnt lgkmcnt(0)
	v_add_f32_e32 v160, v160, v164
	v_add_f32_e32 v161, v161, v165
	v_add_f32_e32 v162, v162, v166
	v_add_f32_e32 v163, v163, v167
	ds_bpermute_b32 v164, v135, v160
	ds_bpermute_b32 v165, v135, v161
	ds_bpermute_b32 v166, v135, v162
	ds_bpermute_b32 v167, v135, v163
	s_waitcnt lgkmcnt(0)
	v_add_f32_e32 v160, v160, v164
	v_add_f32_e32 v161, v161, v165
	v_add_f32_e32 v162, v162, v166
	v_add_f32_e32 v163, v163, v167
	v_cndmask_b32_e64 v164, 0, v160, s[12:13]
	v_cndmask_b32_e64 v165, 0, v161, s[12:13]
	v_cndmask_b32_e64 v166, 0, v162, s[12:13]
	v_cndmask_b32_e64 v167, 0, v163, s[12:13]
	s_mov_b64 exec, 0xffff
	global_store_dword v186, v164, s[6:7]
	global_store_dword v187, v165, s[6:7]
	global_store_dword v188, v166, s[6:7]
	global_store_dword v189, v167, s[6:7]
	s_mov_b64 exec, -1
	s_add_i32 s6, s3, 0x7000
	s_lshl_b32 s6, s6, 12
	s_add_u32 s4, s18, s6
	s_addc_u32 s5, s19, 0
	global_load_dwordx4 v[66:69], v140, s[4:5] nt
	global_load_dwordx4 v[70:73], v140, s[4:5] offset:1024 nt
	global_load_dwordx4 v[74:77], v140, s[4:5] offset:2048 nt
	global_load_dwordx4 v[78:81], v140, s[4:5] offset:3072 nt
	global_load_dwordx4 v[82:85], v141, s[4:5] nt
	global_load_dwordx4 v[86:89], v141, s[4:5] offset:1024 nt
	global_load_dwordx4 v[90:93], v141, s[4:5] offset:2048 nt
	global_load_dwordx4 v[94:97], v141, s[4:5] offset:3072 nt
	global_load_dwordx4 v[98:101], v142, s[4:5] nt
	global_load_dwordx4 v[102:105], v142, s[4:5] offset:1024 nt
	global_load_dwordx4 v[106:109], v142, s[4:5] offset:2048 nt
	global_load_dwordx4 v[110:113], v142, s[4:5] offset:3072 nt
	global_load_dwordx4 v[114:117], v143, s[4:5] nt
	global_load_dwordx4 v[118:121], v143, s[4:5] offset:1024 nt
	global_load_dwordx4 v[122:125], v143, s[4:5] offset:2048 nt
	global_load_dwordx4 v[126:129], v143, s[4:5] offset:3072 nt
	s_waitcnt vmcnt(36)
; __device__ void p0_xconv(const Args& a) {
;     ...
; #pragma unroll
;         for (int r = 0; r < 4; ++r) {
;             const int row = row0 + r * nwv;
;             if (row < MROWS) {
;                 float ss = 0.f;
; #pragma unroll
;                 for (int i = 0; i < 4; ++i) {
;                     const f32x4 x = v[r][i];
;                     ss += (x[0] * x[0] + x[1] * x[1]) + (x[2] * x[2] + x[3] * x[3]);
;                     f16x4 h; h[0] = (f16)x[0]; h[1] = (f16)x[1]; h[2] = (f16)x[2]; h[3] = (f16)x[3];
;                     *(f16x4*)(XH + (size_t)row * DM + i * 256 + lane * 4) = h;
;                 }
; #pragma unroll
;                 for (int o = 1; o < 64; o <<= 1) ss += __shfl_xor(ss, o);
	s_add_i32 s6, s3, 0xa000
	s_lshl_b32 s7, s6, 11
	s_add_u32 s10, s40, s7
	s_addc_u32 s11, s41, 0
	s_lshl_b32 s7, s6, 6
	s_add_u32 s6, s40, s7
	s_addc_u32 s7, s41, 0
	s_add_u32 s6, s6, 0x1f800000
	s_addc_u32 s7, s7, 0
	v_mul_f32_e32 v150, v3, v3
	v_mul_f32_e32 v151, v5, v5
	v_fmac_f32_e32 v150, v2, v2
	v_fmac_f32_e32 v151, v4, v4
	v_add_f32_e32 v160, v150, v151
	v_cvt_pk_f16_f32 v170, v2, v3
	v_cvt_pk_f16_f32 v171, v4, v5
	v_mul_f32_e32 v150, v7, v7
	v_mul_f32_e32 v151, v9, v9
	v_fmac_f32_e32 v150, v6, v6
	v_fmac_f32_e32 v151, v8, v8
	v_add_f32_e32 v152, v150, v151
	v_add_f32_e32 v160, v160, v152
	v_cvt_pk_f16_f32 v172, v6, v7
	v_cvt_pk_f16_f32 v173, v8, v9
	v_mul_f32_e32 v150, v11, v11
	v_mul_f32_e32 v151, v13, v13
	v_fmac_f32_e32 v150, v10, v10
	v_fmac_f32_e32 v151, v12, v12
	v_add_f32_e32 v152, v150, v151
	v_add_f32_e32 v160, v160, v152
	v_cvt_pk_f16_f32 v174, v10, v11
	v_cvt_pk_f16_f32 v175, v12, v13
	v_mul_f32_e32 v150, v15, v15
	v_mul_f32_e32 v151, v17, v17
	v_fmac_f32_e32 v150, v14, v14
	v_fmac_f32_e32 v151, v16, v16
	v_add_f32_e32 v152, v150, v151
	v_add_f32_e32 v160, v160, v152
	v_cvt_pk_f16_f32 v176, v14, v15
	v_cvt_pk_f16_f32 v177, v16, v17
	global_store_dwordx2 v144, v[170:171], s[10:11]
	global_store_dwordx2 v144, v[172:173], s[10:11] offset:512
	global_store_dwordx2 v144, v[174:175], s[10:11] offset:1024
	global_store_dwordx2 v144, v[176:177], s[10:11] offset:1536
	v_mul_f32_e32 v150, v19, v19
	v_mul_f32_e32 v151, v21, v21
	v_fmac_f32_e32 v150, v18, v18
	v_fmac_f32_e32 v151, v20, v20
	v_add_f32_e32 v161, v150, v151
	v_cvt_pk_f16_f32 v178, v18, v19
	v_cvt_pk_f16_f32 v179, v20, v21
	v_mul_f32_e32 v150, v23, v23
	v_mul_f32_e32 v151, v25, v25
	v_fmac_f32_e32 v150, v22, v22
	v_fmac_f32_e32 v151, v24, v24
	v_add_f32_e32 v152, v150, v151
	v_add_f32_e32 v161, v161, v152
	v_cvt_pk_f16_f32 v180, v22, v23
	v_cvt_pk_f16_f32 v181, v24, v25
	v_mul_f32_e32 v150, v27, v27
	v_mul_f32_e32 v151, v29, v29
	v_fmac_f32_e32 v150, v26, v26
	v_fmac_f32_e32 v151, v28, v28
	v_add_f32_e32 v152, v150, v151
	v_add_f32_e32 v161, v161, v152
	v_cvt_pk_f16_f32 v182, v26, v27
	v_cvt_pk_f16_f32 v183, v28, v29
	v_mul_f32_e32 v150, v31, v31
	v_mul_f32_e32 v151, v33, v33
	v_fmac_f32_e32 v150, v30, v30
	v_fmac_f32_e32 v151, v32, v32
	v_add_f32_e32 v152, v150, v151
	v_add_f32_e32 v161, v161, v152
	v_cvt_pk_f16_f32 v184, v30, v31
	v_cvt_pk_f16_f32 v185, v32, v33
	global_store_dwordx2 v145, v[178:179], s[10:11]
	global_store_dwordx2 v145, v[180:181], s[10:11] offset:512
	global_store_dwordx2 v145, v[182:183], s[10:11] offset:1024
	global_store_dwordx2 v145, v[184:185], s[10:11] offset:1536
	v_mul_f32_e32 v150, v35, v35
	v_mul_f32_e32 v151, v37, v37
	v_fmac_f32_e32 v150, v34, v34
	v_fmac_f32_e32 v151, v36, v36
	v_add_f32_e32 v162, v150, v151
	v_cvt_pk_f16_f32 v170, v34, v35
	v_cvt_pk_f16_f32 v171, v36, v37
	v_mul_f32_e32 v150, v39, v39
	v_mul_f32_e32 v151, v41, v41
	v_fmac_f32_e32 v150, v38, v38
	v_fmac_f32_e32 v151, v40, v40
	v_add_f32_e32 v152, v150, v151
	v_add_f32_e32 v162, v162, v152
	v_cvt_pk_f16_f32 v172, v38, v39
	v_cvt_pk_f16_f32 v173, v40, v41
	v_mul_f32_e32 v150, v43, v43
	v_mul_f32_e32 v151, v45, v45
	v_fmac_f32_e32 v150, v42, v42
	v_fmac_f32_e32 v151, v44, v44
	v_add_f32_e32 v152, v150, v151
	v_add_f32_e32 v162, v162, v152
	v_cvt_pk_f16_f32 v174, v42, v43
	v_cvt_pk_f16_f32 v175, v44, v45
	v_mul_f32_e32 v150, v47, v47
	v_mul_f32_e32 v151, v49, v49
	v_fmac_f32_e32 v150, v46, v46
	v_fmac_f32_e32 v151, v48, v48
	v_add_f32_e32 v152, v150, v151
	v_add_f32_e32 v162, v162, v152
	v_cvt_pk_f16_f32 v176, v46, v47
	v_cvt_pk_f16_f32 v177, v48, v49
	global_store_dwordx2 v146, v[170:171], s[10:11]
	global_store_dwordx2 v146, v[172:173], s[10:11] offset:512
	global_store_dwordx2 v146, v[174:175], s[10:11] offset:1024
	global_store_dwordx2 v146, v[176:177], s[10:11] offset:1536
	v_mul_f32_e32 v150, v51, v51
	v_mul_f32_e32 v151, v53, v53
	v_fmac_f32_e32 v150, v50, v50
	v_fmac_f32_e32 v151, v52, v52
	v_add_f32_e32 v163, v150, v151
	v_cvt_pk_f16_f32 v178, v50, v51
	v_cvt_pk_f16_f32 v179, v52, v53
	v_mul_f32_e32 v150, v55, v55
	v_mul_f32_e32 v151, v57, v57
	v_fmac_f32_e32 v150, v54, v54
	v_fmac_f32_e32 v151, v56, v56
	v_add_f32_e32 v152, v150, v151
	v_add_f32_e32 v163, v163, v152
	v_cvt_pk_f16_f32 v180, v54, v55
	v_cvt_pk_f16_f32 v181, v56, v57
	v_mul_f32_e32 v150, v59, v59
	v_mul_f32_e32 v151, v61, v61
	v_fmac_f32_e32 v150, v58, v58
	v_fmac_f32_e32 v151, v60, v60
	v_add_f32_e32 v152, v150, v151
	v_add_f32_e32 v163, v163, v152
	v_cvt_pk_f16_f32 v182, v58, v59
	v_cvt_pk_f16_f32 v183, v60, v61
	v_mul_f32_e32 v150, v63, v63
	v_mul_f32_e32 v151, v65, v65
	v_fmac_f32_e32 v150, v62, v62
	v_fmac_f32_e32 v151, v64, v64
	v_add_f32_e32 v152, v150, v151
	v_add_f32_e32 v163, v163, v152
	v_cvt_pk_f16_f32 v184, v62, v63
	v_cvt_pk_f16_f32 v185, v64, v65
	global_store_dwordx2 v147, v[178:179], s[10:11]
	global_store_dwordx2 v147, v[180:181], s[10:11] offset:512
	global_store_dwordx2 v147, v[182:183], s[10:11] offset:1024
	global_store_dwordx2 v147, v[184:185], s[10:11] offset:1536
	ds_bpermute_b32 v164, v130, v160
	ds_bpermute_b32 v165, v130, v161
	ds_bpermute_b32 v166, v130, v162
	ds_bpermute_b32 v167, v130, v163
	s_waitcnt lgkmcnt(0)
	v_add_f32_e32 v160, v160, v164
	v_add_f32_e32 v161, v161, v165
	v_add_f32_e32 v162, v162, v166
	v_add_f32_e32 v163, v163, v167
	ds_bpermute_b32 v164, v131, v160
	ds_bpermute_b32 v165, v131, v161
	ds_bpermute_b32 v166, v131, v162
	ds_bpermute_b32 v167, v131, v163
	s_waitcnt lgkmcnt(0)
	v_add_f32_e32 v160, v160, v164
	v_add_f32_e32 v161, v161, v165
	v_add_f32_e32 v162, v162, v166
	v_add_f32_e32 v163, v163, v167
	ds_bpermute_b32 v164, v132, v160
	ds_bpermute_b32 v165, v132, v161
	ds_bpermute_b32 v166, v132, v162
	ds_bpermute_b32 v167, v132, v163
	s_waitcnt lgkmcnt(0)
; __device__ void p0_xconv(const Args& a) {
;     ...
; #pragma unroll
;         for (int r = 0; r < 4; ++r) {
;             const int row = row0 + r * nwv;
;             if (row < MROWS) {
;                 float ss = 0.f;
; #pragma unroll
;                 for (int i = 0; i < 4; ++i) {
;                     const f32x4 x = v[r][i];
;                     ss += (x[0] * x[0] + x[1] * x[1]) + (x[2] * x[2] + x[3] * x[3]);
;                     f16x4 h; h[0] = (f16)x[0]; h[1] = (f16)x[1]; h[2] = (f16)x[2]; h[3] = (f16)x[3];
;                     *(f16x4*)(XH + (size_t)row * DM + i * 256 + lane * 4) = h;
;                 }
;     ...
;                 for (int o = 1; o < 64; o <<= 1) ss += __shfl_xor(ss, o);
;                 if (lane < 16) SS[(size_t)row * 16 + lane] = (lane == 0) ? ss : 0.f;
	v_add_f32_e32 v160, v160, v164
	v_add_f32_e32 v161, v161, v165
	v_add_f32_e32 v162, v162, v166
	v_add_f32_e32 v163, v163, v167
	ds_bpermute_b32 v164, v133, v160
	ds_bpermute_b32 v165, v133, v161
	ds_bpermute_b32 v166, v133, v162
	ds_bpermute_b32 v167, v133, v163
	s_waitcnt lgkmcnt(0)
	v_add_f32_e32 v160, v160, v164
	v_add_f32_e32 v161, v161, v165
	v_add_f32_e32 v162, v162, v166
	v_add_f32_e32 v163, v163, v167
	ds_bpermute_b32 v164, v134, v160
	ds_bpermute_b32 v165, v134, v161
	ds_bpermute_b32 v166, v134, v162
	ds_bpermute_b32 v167, v134, v163
	s_waitcnt lgkmcnt(0)
	v_add_f32_e32 v160, v160, v164
	v_add_f32_e32 v161, v161, v165
	v_add_f32_e32 v162, v162, v166
	v_add_f32_e32 v163, v163, v167
	ds_bpermute_b32 v164, v135, v160
	ds_bpermute_b32 v165, v135, v161
	ds_bpermute_b32 v166, v135, v162
	ds_bpermute_b32 v167, v135, v163
	s_waitcnt lgkmcnt(0)
	v_add_f32_e32 v160, v160, v164
	v_add_f32_e32 v161, v161, v165
	v_add_f32_e32 v162, v162, v166
	v_add_f32_e32 v163, v163, v167
	v_cndmask_b32_e64 v164, 0, v160, s[12:13]
	v_cndmask_b32_e64 v165, 0, v161, s[12:13]
	v_cndmask_b32_e64 v166, 0, v162, s[12:13]
	v_cndmask_b32_e64 v167, 0, v163, s[12:13]
	s_mov_b64 exec, 0xffff
	global_store_dword v186, v164, s[6:7]
	global_store_dword v187, v165, s[6:7]
	global_store_dword v188, v166, s[6:7]
	global_store_dword v189, v167, s[6:7]
	s_mov_b64 exec, -1
	s_waitcnt vmcnt(20)
	s_add_i32 s6, s3, 0xb000
	s_lshl_b32 s7, s6, 11
	s_add_u32 s10, s40, s7
	s_addc_u32 s11, s41, 0
	s_lshl_b32 s7, s6, 6
	s_add_u32 s6, s40, s7
	s_addc_u32 s7, s41, 0
	s_add_u32 s6, s6, 0x1f800000
	s_addc_u32 s7, s7, 0
	v_mul_f32_e32 v150, v67, v67
	v_mul_f32_e32 v151, v69, v69
	v_fmac_f32_e32 v150, v66, v66
	v_fmac_f32_e32 v151, v68, v68
	v_add_f32_e32 v160, v150, v151
	v_cvt_pk_f16_f32 v170, v66, v67
	v_cvt_pk_f16_f32 v171, v68, v69
	v_mul_f32_e32 v150, v71, v71
	v_mul_f32_e32 v151, v73, v73
	v_fmac_f32_e32 v150, v70, v70
	v_fmac_f32_e32 v151, v72, v72
	v_add_f32_e32 v152, v150, v151
	v_add_f32_e32 v160, v160, v152
	v_cvt_pk_f16_f32 v172, v70, v71
	v_cvt_pk_f16_f32 v173, v72, v73
	v_mul_f32_e32 v150, v75, v75
	v_mul_f32_e32 v151, v77, v77
	v_fmac_f32_e32 v150, v74, v74
	v_fmac_f32_e32 v151, v76, v76
	v_add_f32_e32 v152, v150, v151
	v_add_f32_e32 v160, v160, v152
	v_cvt_pk_f16_f32 v174, v74, v75
	v_cvt_pk_f16_f32 v175, v76, v77
	v_mul_f32_e32 v150, v79, v79
	v_mul_f32_e32 v151, v81, v81
	v_fmac_f32_e32 v150, v78, v78
	v_fmac_f32_e32 v151, v80, v80
	v_add_f32_e32 v152, v150, v151
	v_add_f32_e32 v160, v160, v152
	v_cvt_pk_f16_f32 v176, v78, v79
	v_cvt_pk_f16_f32 v177, v80, v81
	global_store_dwordx2 v144, v[170:171], s[10:11]
	global_store_dwordx2 v144, v[172:173], s[10:11] offset:512
	global_store_dwordx2 v144, v[174:175], s[10:11] offset:1024
	global_store_dwordx2 v144, v[176:177], s[10:11] offset:1536
	v_mul_f32_e32 v150, v83, v83
	v_mul_f32_e32 v151, v85, v85
	v_fmac_f32_e32 v150, v82, v82
	v_fmac_f32_e32 v151, v84, v84
	v_add_f32_e32 v161, v150, v151
	v_cvt_pk_f16_f32 v178, v82, v83
	v_cvt_pk_f16_f32 v179, v84, v85
	v_mul_f32_e32 v150, v87, v87
	v_mul_f32_e32 v151, v89, v89
	v_fmac_f32_e32 v150, v86, v86
	v_fmac_f32_e32 v151, v88, v88
	v_add_f32_e32 v152, v150, v151
	v_add_f32_e32 v161, v161, v152
	v_cvt_pk_f16_f32 v180, v86, v87
	v_cvt_pk_f16_f32 v181, v88, v89
	v_mul_f32_e32 v150, v91, v91
	v_mul_f32_e32 v151, v93, v93
	v_fmac_f32_e32 v150, v90, v90
	v_fmac_f32_e32 v151, v92, v92
	v_add_f32_e32 v152, v150, v151
	v_add_f32_e32 v161, v161, v152
	v_cvt_pk_f16_f32 v182, v90, v91
	v_cvt_pk_f16_f32 v183, v92, v93
	v_mul_f32_e32 v150, v95, v95
	v_mul_f32_e32 v151, v97, v97
	v_fmac_f32_e32 v150, v94, v94
	v_fmac_f32_e32 v151, v96, v96
	v_add_f32_e32 v152, v150, v151
	v_add_f32_e32 v161, v161, v152
	v_cvt_pk_f16_f32 v184, v94, v95
	v_cvt_pk_f16_f32 v185, v96, v97
	global_store_dwordx2 v145, v[178:179], s[10:11]
	global_store_dwordx2 v145, v[180:181], s[10:11] offset:512
	global_store_dwordx2 v145, v[182:183], s[10:11] offset:1024
	global_store_dwordx2 v145, v[184:185], s[10:11] offset:1536
	v_mul_f32_e32 v150, v99, v99
	v_mul_f32_e32 v151, v101, v101
	v_fmac_f32_e32 v150, v98, v98
	v_fmac_f32_e32 v151, v100, v100
	v_add_f32_e32 v162, v150, v151
	v_cvt_pk_f16_f32 v170, v98, v99
	v_cvt_pk_f16_f32 v171, v100, v101
	v_mul_f32_e32 v150, v103, v103
	v_mul_f32_e32 v151, v105, v105
	v_fmac_f32_e32 v150, v102, v102
	v_fmac_f32_e32 v151, v104, v104
	v_add_f32_e32 v152, v150, v151
	v_add_f32_e32 v162, v162, v152
	v_cvt_pk_f16_f32 v172, v102, v103
	v_cvt_pk_f16_f32 v173, v104, v105
	v_mul_f32_e32 v150, v107, v107
	v_mul_f32_e32 v151, v109, v109
	v_fmac_f32_e32 v150, v106, v106
	v_fmac_f32_e32 v151, v108, v108
	v_add_f32_e32 v152, v150, v151
	v_add_f32_e32 v162, v162, v152
	v_cvt_pk_f16_f32 v174, v106, v107
	v_cvt_pk_f16_f32 v175, v108, v109
	v_mul_f32_e32 v150, v111, v111
	v_mul_f32_e32 v151, v113, v113
	v_fmac_f32_e32 v150, v110, v110
	v_fmac_f32_e32 v151, v112, v112
	v_add_f32_e32 v152, v150, v151
	v_add_f32_e32 v162, v162, v152
	v_cvt_pk_f16_f32 v176, v110, v111
	v_cvt_pk_f16_f32 v177, v112, v113
	global_store_dwordx2 v146, v[170:171], s[10:11]
	global_store_dwordx2 v146, v[172:173], s[10:11] offset:512
	global_store_dwordx2 v146, v[174:175], s[10:11] offset:1024
	global_store_dwordx2 v146, v[176:177], s[10:11] offset:1536
	v_mul_f32_e32 v150, v115, v115
	v_mul_f32_e32 v151, v117, v117
	v_fmac_f32_e32 v150, v114, v114
	v_fmac_f32_e32 v151, v116, v116
	v_add_f32_e32 v163, v150, v151
	v_cvt_pk_f16_f32 v178, v114, v115
	v_cvt_pk_f16_f32 v179, v116, v117
	v_mul_f32_e32 v150, v119, v119
	v_mul_f32_e32 v151, v121, v121
	v_fmac_f32_e32 v150, v118, v118
	v_fmac_f32_e32 v151, v120, v120
	v_add_f32_e32 v152, v150, v151
	v_add_f32_e32 v163, v163, v152
	v_cvt_pk_f16_f32 v180, v118, v119
	v_cvt_pk_f16_f32 v181, v120, v121
	v_mul_f32_e32 v150, v123, v123
	v_mul_f32_e32 v151, v125, v125
	v_fmac_f32_e32 v150, v122, v122
	v_fmac_f32_e32 v151, v124, v124
	v_add_f32_e32 v152, v150, v151
	v_add_f32_e32 v163, v163, v152
	v_cvt_pk_f16_f32 v182, v122, v123
	v_cvt_pk_f16_f32 v183, v124, v125
	v_mul_f32_e32 v150, v127, v127
	v_mul_f32_e32 v151, v129, v129
	v_fmac_f32_e32 v150, v126, v126
	v_fmac_f32_e32 v151, v128, v128
	v_add_f32_e32 v152, v150, v151
	v_add_f32_e32 v163, v163, v152
	v_cvt_pk_f16_f32 v184, v126, v127
	v_cvt_pk_f16_f32 v185, v128, v129
	global_store_dwordx2 v147, v[178:179], s[10:11]
	global_store_dwordx2 v147, v[180:181], s[10:11] offset:512
	global_store_dwordx2 v147, v[182:183], s[10:11] offset:1024
	global_store_dwordx2 v147, v[184:185], s[10:11] offset:1536
	ds_bpermute_b32 v164, v130, v160
	ds_bpermute_b32 v165, v130, v161
	ds_bpermute_b32 v166, v130, v162
	ds_bpermute_b32 v167, v130, v163
	s_waitcnt lgkmcnt(0)
; __device__ void p0_xconv(const Args& a) {
;     ...
;                 for (int o = 1; o < 64; o <<= 1) ss += __shfl_xor(ss, o);
;                 if (lane < 16) SS[(size_t)row * 16 + lane] = (lane == 0) ? ss : 0.f;
	v_add_f32_e32 v160, v160, v164
	v_add_f32_e32 v161, v161, v165
	v_add_f32_e32 v162, v162, v166
	v_add_f32_e32 v163, v163, v167
	ds_bpermute_b32 v164, v131, v160
	ds_bpermute_b32 v165, v131, v161
	ds_bpermute_b32 v166, v131, v162
	ds_bpermute_b32 v167, v131, v163
	s_waitcnt lgkmcnt(0)
	v_add_f32_e32 v160, v160, v164
	v_add_f32_e32 v161, v161, v165
	v_add_f32_e32 v162, v162, v166
	v_add_f32_e32 v163, v163, v167
	ds_bpermute_b32 v164, v132, v160
	ds_bpermute_b32 v165, v132, v161
	ds_bpermute_b32 v166, v132, v162
	ds_bpermute_b32 v167, v132, v163
	s_waitcnt lgkmcnt(0)
	v_add_f32_e32 v160, v160, v164
	v_add_f32_e32 v161, v161, v165
	v_add_f32_e32 v162, v162, v166
	v_add_f32_e32 v163, v163, v167
	ds_bpermute_b32 v164, v133, v160
	ds_bpermute_b32 v165, v133, v161
	ds_bpermute_b32 v166, v133, v162
	ds_bpermute_b32 v167, v133, v163
	s_waitcnt lgkmcnt(0)
	v_add_f32_e32 v160, v160, v164
	v_add_f32_e32 v161, v161, v165
	v_add_f32_e32 v162, v162, v166
	v_add_f32_e32 v163, v163, v167
	ds_bpermute_b32 v164, v134, v160
	ds_bpermute_b32 v165, v134, v161
	ds_bpermute_b32 v166, v134, v162
	ds_bpermute_b32 v167, v134, v163
	s_waitcnt lgkmcnt(0)
	v_add_f32_e32 v160, v160, v164
	v_add_f32_e32 v161, v161, v165
	v_add_f32_e32 v162, v162, v166
	v_add_f32_e32 v163, v163, v167
	ds_bpermute_b32 v164, v135, v160
	ds_bpermute_b32 v165, v135, v161
	ds_bpermute_b32 v166, v135, v162
	ds_bpermute_b32 v167, v135, v163
	s_waitcnt lgkmcnt(0)
	v_add_f32_e32 v160, v160, v164
	v_add_f32_e32 v161, v161, v165
	v_add_f32_e32 v162, v162, v166
	v_add_f32_e32 v163, v163, v167
	v_cndmask_b32_e64 v164, 0, v160, s[12:13]
	v_cndmask_b32_e64 v165, 0, v161, s[12:13]
	v_cndmask_b32_e64 v166, 0, v162, s[12:13]
	v_cndmask_b32_e64 v167, 0, v163, s[12:13]
	s_mov_b64 exec, 0xffff
	global_store_dword v186, v164, s[6:7]
	global_store_dword v187, v165, s[6:7]
	global_store_dword v188, v166, s[6:7]
	global_store_dword v189, v167, s[6:7]
	s_mov_b64 exec, -1
	s_barrier
	s_branch .LBB0_112
